# rbacc
# speedup vs baseline: 1.0129x; 1.0129x over previous
;     __device__ bool next(int i, Unit& u) const { Unit t; if (!so.next(i / 3, t)) return false; const int br = i % 3; u.pm = br * 64 + t.pm; u.pn = br * 8 + t.pn; return true; }
; template <class Epi, class Sched, bool ALIGN_EPI = false, bool SP2 = false>
; __device__ __forceinline__ void gemm_phase(PG8_LAS unsigned char* lds, const Gemm g, const Sched& S, const Epi& E, const int tid_in) {
;     ...
;     f32x4 acc[2][2][4][2];
; #pragma unroll
;     for (int a = 0; a < 2; ++a)
; #pragma unroll
;         for (int b = 0; b < 2; ++b)
; #pragma unroll
;             for (int m = 0; m < 4; ++m)
; #pragma unroll
;                 for (int n = 0; n < 2; ++n) acc[a][b][m][n] = (f32x4){0.f, 0.f, 0.f, 0.f};
.LBB0_84:
	s_ashr_i32 s26, s36, 3
	s_add_i32 s26, s38, s26
	s_ashr_i32 s27, s26, 31
	s_lshr_b32 s27, s27, 28
	s_add_i32 s27, s26, s27
	s_ashr_i32 s36, s27, 4
	s_lshl_b32 s36, s36, 1
	s_sub_i32 s37, 64, s36
	s_min_i32 s37, s37, 2
	s_abs_i32 s38, s37
	v_cvt_f32_u32_e32 v246, s38
	s_sub_i32 s40, 0, s38
	s_and_b32 s27, s27, -16
	s_sub_i32 s26, s26, s27
	v_rcp_iflag_f32_e32 v246, v246
	s_abs_i32 s27, s26
	s_xor_b32 s39, s26, s37
	s_ashr_i32 s39, s39, 31
	v_mul_f32_e32 v246, 0x4f7ffffe, v246
	v_cvt_u32_f32_e32 v246, v246
	s_mul_i32 s9, s9, 3
	v_readfirstlane_b32 s41, v246
	s_mul_i32 s40, s40, s41
	s_mul_hi_u32 s40, s41, s40
	s_add_i32 s41, s41, s40
	s_mul_hi_u32 s40, s27, s41
	s_mul_i32 s41, s40, s38
	s_sub_i32 s27, s27, s41
	s_add_i32 s43, s40, 1
	s_sub_i32 s41, s27, s38
	s_cmp_ge_u32 s27, s38
	s_cselect_b32 s40, s43, s40
	s_cselect_b32 s27, s41, s27
	s_add_i32 s41, s40, 1
	s_cmp_ge_u32 s27, s38
	s_cselect_b32 s27, s41, s40
	s_xor_b32 s27, s27, s39
	s_sub_i32 s27, s27, s39
	s_mul_i32 s37, s27, s37
	s_sub_i32 s9, s86, s9
	s_sub_i32 s26, s26, s37
	s_lshl_b32 s37, s9, 6
	s_add_i32 s26, s26, s37
	s_lshl_b32 s9, s9, 3
	s_add_i32 s26, s26, s36
	s_add_i32 s36, s27, s9
.LBB0_85:
	s_ashr_i32 s27, s26, 31
	s_lshl_b64 s[38:39], s[26:27], 18
	s_add_u32 s38, s50, s38
	s_addc_u32 s39, s51, s39
	s_and_b64 s[40:41], s[6:7], exec
	s_cselect_b32 s9, s39, s45
	s_cselect_b32 s27, s38, s44
	s_ashr_i32 s37, s36, 31
	s_lshl_b64 s[40:41], s[36:37], 18
	s_add_u32 s40, s25, s40
	s_addc_u32 s41, s34, s41
	s_and_b64 s[48:49], s[6:7], exec
	s_cselect_b32 s37, s41, s47
	s_cselect_b32 s43, s40, s46
	s_add_u32 s44, s44, 0x20080
	s_addc_u32 s45, s45, 0
	s_add_u32 s72, s46, 0x100
	s_addc_u32 s87, s47, 0
	s_mov_b32 s88, -2
	s_cmp_gt_u32 s42, 63
	s_cbranch_scc1 .Lrb_nozero
	v_mov_b32_e32 v2, 0
	v_mov_b32_e32 v3, v2
	v_mov_b32_e32 v4, v2
	v_mov_b32_e32 v5, v2
	v_mov_b32_e32 v6, v2
	v_mov_b32_e32 v7, v2
	v_mov_b32_e32 v8, v2
	v_mov_b32_e32 v9, v2
	v_mov_b32_e32 v18, v2
	v_mov_b32_e32 v19, v2
	v_mov_b32_e32 v20, v2
	v_mov_b32_e32 v21, v2
	v_mov_b32_e32 v22, v2
	v_mov_b32_e32 v23, v2
	v_mov_b32_e32 v24, v2
	v_mov_b32_e32 v25, v2
	v_mov_b32_e32 v34, v2
	v_mov_b32_e32 v35, v2
	v_mov_b32_e32 v36, v2
	v_mov_b32_e32 v37, v2
	v_mov_b32_e32 v38, v2
	v_mov_b32_e32 v39, v2
	v_mov_b32_e32 v40, v2
	v_mov_b32_e32 v41, v2
	v_mov_b32_e32 v50, v2
	v_mov_b32_e32 v51, v2
	v_mov_b32_e32 v52, v2
	v_mov_b32_e32 v53, v2
	v_mov_b32_e32 v54, v2
	v_mov_b32_e32 v55, v2
	v_mov_b32_e32 v56, v2
	v_mov_b32_e32 v57, v2
	v_mov_b32_e32 v10, v2
	v_mov_b32_e32 v11, v2
	v_mov_b32_e32 v12, v2
	v_mov_b32_e32 v13, v2
	v_mov_b32_e32 v14, v2
	v_mov_b32_e32 v15, v2
	v_mov_b32_e32 v16, v2
	v_mov_b32_e32 v17, v2
	v_mov_b32_e32 v26, v2
	v_mov_b32_e32 v27, v2
	v_mov_b32_e32 v28, v2
	v_mov_b32_e32 v29, v2
	v_mov_b32_e32 v30, v2
	v_mov_b32_e32 v31, v2
	v_mov_b32_e32 v32, v2
	v_mov_b32_e32 v33, v2
	v_mov_b32_e32 v42, v2
	v_mov_b32_e32 v43, v2
	v_mov_b32_e32 v44, v2
	v_mov_b32_e32 v45, v2
	v_mov_b32_e32 v46, v2
	v_mov_b32_e32 v47, v2
	v_mov_b32_e32 v48, v2
	v_mov_b32_e32 v49, v2
	v_mov_b32_e32 v58, v2
	v_mov_b32_e32 v59, v2
	v_mov_b32_e32 v60, v2
	v_mov_b32_e32 v61, v2
	v_mov_b32_e32 v62, v2
	v_mov_b32_e32 v63, v2
	v_mov_b32_e32 v64, v2
	v_mov_b32_e32 v65, v2
	v_mov_b32_e32 v66, v2
	v_mov_b32_e32 v67, v2
	v_mov_b32_e32 v68, v2
	v_mov_b32_e32 v69, v2
	v_mov_b32_e32 v70, v2
	v_mov_b32_e32 v71, v2
	v_mov_b32_e32 v72, v2
	v_mov_b32_e32 v73, v2
	v_mov_b32_e32 v82, v2
	v_mov_b32_e32 v83, v2
	v_mov_b32_e32 v84, v2
	v_mov_b32_e32 v85, v2
	v_mov_b32_e32 v86, v2
	v_mov_b32_e32 v87, v2
	v_mov_b32_e32 v88, v2
	v_mov_b32_e32 v89, v2
	v_mov_b32_e32 v98, v2
	v_mov_b32_e32 v99, v2
	v_mov_b32_e32 v100, v2
	v_mov_b32_e32 v101, v2
	v_mov_b32_e32 v102, v2
	v_mov_b32_e32 v103, v2
	v_mov_b32_e32 v104, v2
	v_mov_b32_e32 v105, v2
	v_mov_b32_e32 v114, v2
	v_mov_b32_e32 v115, v2
	v_mov_b32_e32 v116, v2
	v_mov_b32_e32 v117, v2
	v_mov_b32_e32 v118, v2
	v_mov_b32_e32 v119, v2
	v_mov_b32_e32 v120, v2
	v_mov_b32_e32 v121, v2
	v_mov_b32_e32 v74, v2
	v_mov_b32_e32 v75, v2
	v_mov_b32_e32 v76, v2
	v_mov_b32_e32 v77, v2
	v_mov_b32_e32 v78, v2
	v_mov_b32_e32 v79, v2
	v_mov_b32_e32 v80, v2
	v_mov_b32_e32 v81, v2
	v_mov_b32_e32 v90, v2
	v_mov_b32_e32 v91, v2
	v_mov_b32_e32 v92, v2
	v_mov_b32_e32 v93, v2
	v_mov_b32_e32 v94, v2
	v_mov_b32_e32 v95, v2
	v_mov_b32_e32 v96, v2
	v_mov_b32_e32 v97, v2
	v_mov_b32_e32 v106, v2
	v_mov_b32_e32 v107, v2
	v_mov_b32_e32 v108, v2
	v_mov_b32_e32 v109, v2
	v_mov_b32_e32 v110, v2
	v_mov_b32_e32 v111, v2
	v_mov_b32_e32 v112, v2
	v_mov_b32_e32 v113, v2
	v_mov_b32_e32 v122, v2
	v_mov_b32_e32 v123, v2
	v_mov_b32_e32 v124, v2
	v_mov_b32_e32 v125, v2
	v_mov_b32_e32 v126, v2
	v_mov_b32_e32 v127, v2
	v_mov_b32_e32 v128, v2
	v_mov_b32_e32 v129, v2
; #define PG8_STAGE(bufoff, gbase, voff) do { _Pragma("unroll") for (int _i = 0; _i < 2; ++_i) \
;         __builtin_amdgcn_global_load_lds((const unsigned*)((const char*)(gbase) + (voff)[_i]), (PG8_LAS unsigned*)(lds + (bufoff) + ldsw + _i * 8192), 16, 0, 0); } while (0)
; #define PG8_LDA(dst, b, h) do { _Pragma("unroll") for (int m = 0; m < 4; ++m) _Pragma("unroll") for (int k = 0; k < 2; ++k) dst[m][k] = *(const PG8_LAS bf16x8*)(lds + PG8_SA(b, h) + aoff + m * 2048 + k * 1024); } while (0)
; #define PG8_LDB(dst, b, h) do { _Pragma("unroll") for (int n = 0; n < 2; ++n) _Pragma("unroll") for (int k = 0; k < 2; ++k) dst[n][k] = *(const PG8_LAS bf16x8*)(lds + PG8_SB(b, h) + boff + n * 2048 + k * 1024); } while (0)
; #define PG8_MMA(ai, bj, At, Bt) do { __builtin_amdgcn_s_setprio(1); _Pragma("unroll") for (int m = 0; m < 4; ++m) _Pragma("unroll") for (int n = 0; n < 2; ++n) _Pragma("unroll") for (int k = 0; k < 2; ++k) \
;         acc[ai][bj][m][n] = __builtin_amdgcn_mfma_f32_16x16x32_bf16(Bt[n][k], At[m][k], acc[ai][bj][m][n], 0, 0, 0); __builtin_amdgcn_s_setprio(0); } while (0)
; #define PG8_WAIT_V(n) asm volatile("s_waitcnt vmcnt(" #n ")" ::: "memory")
; #define PG8_WAIT_L(n) asm volatile("s_waitcnt lgkmcnt(" #n ")" ::: "memory")
; #define PG8_BAR __builtin_amdgcn_s_barrier()
; #define PG8_SCHED __builtin_amdgcn_sched_barrier(0)
; template <class Epi, class Sched, bool ALIGN_EPI = false, bool SP2 = false>
; __device__ __forceinline__ void gemm_phase(PG8_LAS unsigned char* lds, const Gemm g, const Sched& S, const Epi& E, const int tid_in) {
;     ...
;             if constexpr (SP2) {
;             PG8_LDB(B0, 0, 0); PG8_LDB(B1, 0, 1); PG8_SCHED; PG8_LDA(At, 0, 0); PG8_STAGE(PG8_SA(1, 1), a1 + hstep, voffA);
;             PG8_WAIT_V(8); PG8_WAIT_L(0); PG8_BAR; PG8_MMA(0, 0, At, B0); PG8_MMA(0, 1, At, B1); PG8_BAR; PG8_SCHED;
;             PG8_LDA(At, 0, 1); PG8_STAGE(PG8_SB(0, 0), b2, voffB); PG8_STAGE(PG8_SB(0, 1), b2 + hstep, voffB); PG8_STAGE(PG8_SA(0, 0), a2, voffA);
;             PG8_WAIT_V(8); PG8_WAIT_L(0); PG8_BAR; PG8_MMA(1, 0, At, B0); PG8_MMA(1, 1, At, B1); PG8_BAR; PG8_SCHED;
.Lrb_nozero:
.LBB0_86:
	s_add_u32 s46, s44, 0xfffe0080
	s_addc_u32 s47, s45, -1
	s_add_i32 s89, 0, 0x10000
	s_cmp_eq_u32 s88, 4
	s_cselect_b32 s49, s9, s47
	s_cselect_b32 s48, s27, s46
	s_cselect_b32 s47, s37, s87
	s_cselect_b32 s46, s43, s72
	s_add_i32 s31, 0, 0x14000
	v_add_u32_e32 v142, s89, v240
	v_add_u32_e32 v158, s31, v240
	ds_read_b128 v[130:133], v142
	ds_read_b128 v[134:137], v142 offset:1024
	ds_read_b128 v[138:141], v142 offset:2048
	ds_read_b128 v[142:145], v142 offset:3072
	ds_read_b128 v[146:149], v158
	ds_read_b128 v[150:153], v158 offset:1024
	ds_read_b128 v[154:157], v158 offset:2048
	ds_read_b128 v[158:161], v158 offset:3072
	v_lshl_add_u64 v[218:219], s[44:45], 0, v[182:183]
	s_add_i32 m0, s53, 0xc000
	ds_read_b128 v[186:189], v241
	ds_read_b128 v[190:193], v241 offset:1024
	ds_read_b128 v[194:197], v241 offset:2048
	ds_read_b128 v[198:201], v241 offset:3072
	ds_read_b128 v[202:205], v241 offset:4096
	ds_read_b128 v[206:209], v241 offset:5120
	ds_read_b128 v[210:213], v241 offset:6144
	ds_read_b128 v[214:217], v241 offset:7168
	global_load_lds_dwordx4 v[218:219], off
	v_lshl_add_u64 v[218:219], s[44:45], 0, v[184:185]
	s_add_i32 m0, s53, 0xe000
	s_nop 0
	global_load_lds_dwordx4 v[218:219], off
	s_waitcnt vmcnt(8)
	s_waitcnt lgkmcnt(0)
	s_barrier
	s_setprio 1
	s_waitcnt lgkmcnt(0)
	v_mfma_f32_16x16x32_bf16 v[126:129], v[130:133], v[186:189], v[126:129]
	v_mfma_f32_16x16x32_bf16 v[122:125], v[138:141], v[186:189], v[122:125]
	v_mfma_f32_16x16x32_bf16 v[110:113], v[130:133], v[194:197], v[110:113]
	v_mfma_f32_16x16x32_bf16 v[106:109], v[138:141], v[194:197], v[106:109]
	v_mfma_f32_16x16x32_bf16 v[94:97], v[130:133], v[202:205], v[94:97]
	v_mfma_f32_16x16x32_bf16 v[90:93], v[138:141], v[202:205], v[90:93]
	v_mfma_f32_16x16x32_bf16 v[78:81], v[130:133], v[210:213], v[78:81]
	v_mfma_f32_16x16x32_bf16 v[74:77], v[138:141], v[210:213], v[74:77]
	v_mfma_f32_16x16x32_bf16 v[126:129], v[134:137], v[190:193], v[126:129]
	v_mfma_f32_16x16x32_bf16 v[122:125], v[142:145], v[190:193], v[122:125]
	v_mfma_f32_16x16x32_bf16 v[110:113], v[134:137], v[198:201], v[110:113]
	v_mfma_f32_16x16x32_bf16 v[106:109], v[142:145], v[198:201], v[106:109]
	v_mfma_f32_16x16x32_bf16 v[94:97], v[134:137], v[206:209], v[94:97]
	v_mfma_f32_16x16x32_bf16 v[90:93], v[142:145], v[206:209], v[90:93]
	v_mfma_f32_16x16x32_bf16 v[78:81], v[134:137], v[214:217], v[78:81]
	v_mfma_f32_16x16x32_bf16 v[74:77], v[142:145], v[214:217], v[74:77]
	s_setprio 0
	s_setprio 1
	v_mfma_f32_16x16x32_bf16 v[118:121], v[146:149], v[186:189], v[118:121]
	v_mfma_f32_16x16x32_bf16 v[114:117], v[154:157], v[186:189], v[114:117]
	v_mfma_f32_16x16x32_bf16 v[102:105], v[146:149], v[194:197], v[102:105]
	v_mfma_f32_16x16x32_bf16 v[98:101], v[154:157], v[194:197], v[98:101]
	v_mfma_f32_16x16x32_bf16 v[86:89], v[146:149], v[202:205], v[86:89]
	v_mfma_f32_16x16x32_bf16 v[82:85], v[154:157], v[202:205], v[82:85]
	v_mfma_f32_16x16x32_bf16 v[70:73], v[146:149], v[210:213], v[70:73]
	v_mfma_f32_16x16x32_bf16 v[66:69], v[154:157], v[210:213], v[66:69]
	v_mfma_f32_16x16x32_bf16 v[118:121], v[150:153], v[190:193], v[118:121]
	v_mfma_f32_16x16x32_bf16 v[114:117], v[158:161], v[190:193], v[114:117]
	v_mfma_f32_16x16x32_bf16 v[102:105], v[150:153], v[198:201], v[102:105]
	v_mfma_f32_16x16x32_bf16 v[98:101], v[158:161], v[198:201], v[98:101]
	v_mfma_f32_16x16x32_bf16 v[86:89], v[150:153], v[206:209], v[86:89]
	v_mfma_f32_16x16x32_bf16 v[82:85], v[158:161], v[206:209], v[82:85]
	v_mfma_f32_16x16x32_bf16 v[70:73], v[150:153], v[214:217], v[70:73]
	v_mfma_f32_16x16x32_bf16 v[66:69], v[158:161], v[214:217], v[66:69]
	s_setprio 0
	s_barrier
	s_add_i32 s89, s89, s52
	v_lshl_add_u64 v[218:219], s[46:47], 0, v[0:1]
	s_mov_b32 m0, s89
	ds_read_b128 v[186:189], v241 offset:16384
	ds_read_b128 v[190:193], v241 offset:17408
	ds_read_b128 v[194:197], v241 offset:18432
	ds_read_b128 v[198:201], v241 offset:19456
	ds_read_b128 v[202:205], v241 offset:20480
	ds_read_b128 v[206:209], v241 offset:21504
	ds_read_b128 v[210:213], v241 offset:22528
	ds_read_b128 v[214:217], v241 offset:23552
	global_load_lds_dwordx4 v[218:219], off
	s_add_i32 m0, s89, 0x2000
	s_add_u32 vcc_lo, s46, 0x20000
	v_lshl_add_u64 v[220:221], s[46:47], 0, v[180:181]
	s_addc_u32 vcc_hi, s47, 0
	s_add_i32 s31, s31, s52
	global_load_lds_dwordx4 v[220:221], off
	v_lshl_add_u64 v[222:223], vcc, 0, v[0:1]
	s_mov_b32 m0, s31
	v_lshl_add_u64 v[224:225], s[48:49], 0, v[178:179]
	global_load_lds_dwordx4 v[222:223], off
	v_lshl_add_u64 v[222:223], vcc, 0, v[180:181]
	s_add_i32 m0, s31, 0x2000
	s_nop 0
	global_load_lds_dwordx4 v[222:223], off
	v_lshl_add_u64 v[222:223], s[48:49], 0, v[176:177]
	s_mov_b32 m0, s53
	s_nop 0
	global_load_lds_dwordx4 v[222:223], off
	s_mov_b32 m0, s54
	s_nop 0
	global_load_lds_dwordx4 v[224:225], off
	s_waitcnt vmcnt(8)
	s_waitcnt lgkmcnt(0)
	s_barrier
; #define PG8_STAGE(bufoff, gbase, voff) do { _Pragma("unroll") for (int _i = 0; _i < 2; ++_i) \
;         __builtin_amdgcn_global_load_lds((const unsigned*)((const char*)(gbase) + (voff)[_i]), (PG8_LAS unsigned*)(lds + (bufoff) + ldsw + _i * 8192), 16, 0, 0); } while (0)
; #define PG8_LDA(dst, b, h) do { _Pragma("unroll") for (int m = 0; m < 4; ++m) _Pragma("unroll") for (int k = 0; k < 2; ++k) dst[m][k] = *(const PG8_LAS bf16x8*)(lds + PG8_SA(b, h) + aoff + m * 2048 + k * 1024); } while (0)
; #define PG8_LDB(dst, b, h) do { _Pragma("unroll") for (int n = 0; n < 2; ++n) _Pragma("unroll") for (int k = 0; k < 2; ++k) dst[n][k] = *(const PG8_LAS bf16x8*)(lds + PG8_SB(b, h) + boff + n * 2048 + k * 1024); } while (0)
; #define PG8_MMA(ai, bj, At, Bt) do { __builtin_amdgcn_s_setprio(1); _Pragma("unroll") for (int m = 0; m < 4; ++m) _Pragma("unroll") for (int n = 0; n < 2; ++n) _Pragma("unroll") for (int k = 0; k < 2; ++k) \
;         acc[ai][bj][m][n] = __builtin_amdgcn_mfma_f32_16x16x32_bf16(Bt[n][k], At[m][k], acc[ai][bj][m][n], 0, 0, 0); __builtin_amdgcn_s_setprio(0); } while (0)
; #define PG8_WAIT_V(n) asm volatile("s_waitcnt vmcnt(" #n ")" ::: "memory")
; #define PG8_WAIT_L(n) asm volatile("s_waitcnt lgkmcnt(" #n ")" ::: "memory")
; #define PG8_BAR __builtin_amdgcn_s_barrier()
; #define PG8_SCHED __builtin_amdgcn_sched_barrier(0)
; template <class Epi, class Sched, bool ALIGN_EPI = false, bool SP2 = false>
; __device__ __forceinline__ void gemm_phase(PG8_LAS unsigned char* lds, const Gemm g, const Sched& S, const Epi& E, const int tid_in) {
;     ...
;             PG8_WAIT_V(8); PG8_WAIT_L(0); PG8_BAR; PG8_MMA(1, 0, At, B0); PG8_MMA(1, 1, At, B1); PG8_BAR; PG8_SCHED;
;             PG8_LDB(B0, 1, 0); PG8_LDB(B1, 1, 1); PG8_SCHED; PG8_LDA(At, 1, 0); PG8_STAGE(PG8_SA(0, 1), a2 + hstep, voffA);
;             PG8_WAIT_V(8); PG8_WAIT_L(0); PG8_BAR; PG8_MMA(0, 0, At, B0); PG8_MMA(0, 1, At, B1); PG8_BAR; PG8_SCHED;
	s_setprio 1
	s_waitcnt lgkmcnt(0)
	v_mfma_f32_16x16x32_bf16 v[62:65], v[130:133], v[186:189], v[62:65]
	v_mfma_f32_16x16x32_bf16 v[58:61], v[138:141], v[186:189], v[58:61]
	v_mfma_f32_16x16x32_bf16 v[46:49], v[130:133], v[194:197], v[46:49]
	v_mfma_f32_16x16x32_bf16 v[42:45], v[138:141], v[194:197], v[42:45]
	v_mfma_f32_16x16x32_bf16 v[30:33], v[130:133], v[202:205], v[30:33]
	v_mfma_f32_16x16x32_bf16 v[26:29], v[138:141], v[202:205], v[26:29]
	v_mfma_f32_16x16x32_bf16 v[14:17], v[130:133], v[210:213], v[14:17]
	v_mfma_f32_16x16x32_bf16 v[10:13], v[138:141], v[210:213], v[10:13]
	v_mfma_f32_16x16x32_bf16 v[62:65], v[134:137], v[190:193], v[62:65]
	v_mfma_f32_16x16x32_bf16 v[58:61], v[142:145], v[190:193], v[58:61]
	v_mfma_f32_16x16x32_bf16 v[46:49], v[134:137], v[198:201], v[46:49]
	v_mfma_f32_16x16x32_bf16 v[42:45], v[142:145], v[198:201], v[42:45]
	v_mfma_f32_16x16x32_bf16 v[30:33], v[134:137], v[206:209], v[30:33]
	v_mfma_f32_16x16x32_bf16 v[26:29], v[142:145], v[206:209], v[26:29]
	v_mfma_f32_16x16x32_bf16 v[14:17], v[134:137], v[214:217], v[14:17]
	v_mfma_f32_16x16x32_bf16 v[10:13], v[142:145], v[214:217], v[10:13]
	s_setprio 0
	s_setprio 1
	v_mfma_f32_16x16x32_bf16 v[54:57], v[146:149], v[186:189], v[54:57]
	v_mfma_f32_16x16x32_bf16 v[50:53], v[154:157], v[186:189], v[50:53]
	v_mfma_f32_16x16x32_bf16 v[38:41], v[146:149], v[194:197], v[38:41]
	v_mfma_f32_16x16x32_bf16 v[34:37], v[154:157], v[194:197], v[34:37]
	v_mfma_f32_16x16x32_bf16 v[22:25], v[146:149], v[202:205], v[22:25]
	v_mfma_f32_16x16x32_bf16 v[18:21], v[154:157], v[202:205], v[18:21]
	v_mfma_f32_16x16x32_bf16 v[6:9], v[146:149], v[210:213], v[6:9]
	v_mfma_f32_16x16x32_bf16 v[2:5], v[154:157], v[210:213], v[2:5]
	v_mfma_f32_16x16x32_bf16 v[54:57], v[150:153], v[190:193], v[54:57]
	v_mfma_f32_16x16x32_bf16 v[50:53], v[158:161], v[190:193], v[50:53]
	v_mfma_f32_16x16x32_bf16 v[38:41], v[150:153], v[198:201], v[38:41]
	v_mfma_f32_16x16x32_bf16 v[34:37], v[158:161], v[198:201], v[34:37]
	v_mfma_f32_16x16x32_bf16 v[22:25], v[150:153], v[206:209], v[22:25]
	v_mfma_f32_16x16x32_bf16 v[18:21], v[158:161], v[206:209], v[18:21]
	v_mfma_f32_16x16x32_bf16 v[6:9], v[150:153], v[214:217], v[6:9]
	v_mfma_f32_16x16x32_bf16 v[2:5], v[158:161], v[214:217], v[2:5]
	s_setprio 0
	s_barrier
	s_add_i32 s31, 0, 0x18000
	s_add_i32 s89, 0, 0x1c000
	v_add_u32_e32 v142, s31, v240
	v_add_u32_e32 v158, s89, v240
	ds_read_b128 v[130:133], v142
	ds_read_b128 v[134:137], v142 offset:1024
	ds_read_b128 v[138:141], v142 offset:2048
	ds_read_b128 v[142:145], v142 offset:3072
	ds_read_b128 v[146:149], v158
	ds_read_b128 v[150:153], v158 offset:1024
	ds_read_b128 v[154:157], v158 offset:2048
	ds_read_b128 v[158:161], v158 offset:3072
	s_add_u32 s48, s48, 0x20000
	s_addc_u32 s49, s49, 0
	s_mov_b32 m0, s55
	v_lshl_add_u64 v[226:227], s[48:49], 0, v[176:177]
	ds_read_b128 v[186:189], v241 offset:32768
	ds_read_b128 v[190:193], v241 offset:33792
	ds_read_b128 v[194:197], v241 offset:34816
	ds_read_b128 v[198:201], v241 offset:35840
	ds_read_b128 v[202:205], v241 offset:36864
	ds_read_b128 v[206:209], v241 offset:37888
	ds_read_b128 v[210:213], v241 offset:38912
	ds_read_b128 v[214:217], v241 offset:39936
	global_load_lds_dwordx4 v[226:227], off
	v_lshl_add_u64 v[226:227], s[48:49], 0, v[178:179]
	s_mov_b32 m0, s62
	s_nop 0
	global_load_lds_dwordx4 v[226:227], off
	s_waitcnt vmcnt(8)
	s_waitcnt lgkmcnt(0)
	s_barrier
	s_setprio 1
	s_waitcnt lgkmcnt(0)
	v_mfma_f32_16x16x32_bf16 v[126:129], v[130:133], v[186:189], v[126:129]
	v_mfma_f32_16x16x32_bf16 v[122:125], v[138:141], v[186:189], v[122:125]
	v_mfma_f32_16x16x32_bf16 v[110:113], v[130:133], v[194:197], v[110:113]
	v_mfma_f32_16x16x32_bf16 v[106:109], v[138:141], v[194:197], v[106:109]
	v_mfma_f32_16x16x32_bf16 v[94:97], v[130:133], v[202:205], v[94:97]
	v_mfma_f32_16x16x32_bf16 v[90:93], v[138:141], v[202:205], v[90:93]
	v_mfma_f32_16x16x32_bf16 v[78:81], v[130:133], v[210:213], v[78:81]
	v_mfma_f32_16x16x32_bf16 v[74:77], v[138:141], v[210:213], v[74:77]
	v_mfma_f32_16x16x32_bf16 v[126:129], v[134:137], v[190:193], v[126:129]
	v_mfma_f32_16x16x32_bf16 v[122:125], v[142:145], v[190:193], v[122:125]
	v_mfma_f32_16x16x32_bf16 v[110:113], v[134:137], v[198:201], v[110:113]
	v_mfma_f32_16x16x32_bf16 v[106:109], v[142:145], v[198:201], v[106:109]
	v_mfma_f32_16x16x32_bf16 v[94:97], v[134:137], v[206:209], v[94:97]
	v_mfma_f32_16x16x32_bf16 v[90:93], v[142:145], v[206:209], v[90:93]
	v_mfma_f32_16x16x32_bf16 v[78:81], v[134:137], v[214:217], v[78:81]
	v_mfma_f32_16x16x32_bf16 v[74:77], v[142:145], v[214:217], v[74:77]
	s_setprio 0
	s_setprio 1
	v_mfma_f32_16x16x32_bf16 v[118:121], v[146:149], v[186:189], v[118:121]
	v_mfma_f32_16x16x32_bf16 v[114:117], v[154:157], v[186:189], v[114:117]
	v_mfma_f32_16x16x32_bf16 v[102:105], v[146:149], v[194:197], v[102:105]
	v_mfma_f32_16x16x32_bf16 v[98:101], v[154:157], v[194:197], v[98:101]
	v_mfma_f32_16x16x32_bf16 v[86:89], v[146:149], v[202:205], v[86:89]
	v_mfma_f32_16x16x32_bf16 v[82:85], v[154:157], v[202:205], v[82:85]
	v_mfma_f32_16x16x32_bf16 v[70:73], v[146:149], v[210:213], v[70:73]
	v_mfma_f32_16x16x32_bf16 v[66:69], v[154:157], v[210:213], v[66:69]
	v_mfma_f32_16x16x32_bf16 v[118:121], v[150:153], v[190:193], v[118:121]
	v_mfma_f32_16x16x32_bf16 v[114:117], v[158:161], v[190:193], v[114:117]
	v_mfma_f32_16x16x32_bf16 v[102:105], v[150:153], v[198:201], v[102:105]
	v_mfma_f32_16x16x32_bf16 v[98:101], v[158:161], v[198:201], v[98:101]
	v_mfma_f32_16x16x32_bf16 v[86:89], v[150:153], v[206:209], v[86:89]
	v_mfma_f32_16x16x32_bf16 v[82:85], v[158:161], v[206:209], v[82:85]
	v_mfma_f32_16x16x32_bf16 v[70:73], v[150:153], v[214:217], v[70:73]
	v_mfma_f32_16x16x32_bf16 v[66:69], v[158:161], v[214:217], v[66:69]
	s_setprio 0
	s_barrier
; #define PG8_STAGE(bufoff, gbase, voff) do { _Pragma("unroll") for (int _i = 0; _i < 2; ++_i) \
;         __builtin_amdgcn_global_load_lds((const unsigned*)((const char*)(gbase) + (voff)[_i]), (PG8_LAS unsigned*)(lds + (bufoff) + ldsw + _i * 8192), 16, 0, 0); } while (0)
; #define PG8_LDA(dst, b, h) do { _Pragma("unroll") for (int m = 0; m < 4; ++m) _Pragma("unroll") for (int k = 0; k < 2; ++k) dst[m][k] = *(const PG8_LAS bf16x8*)(lds + PG8_SA(b, h) + aoff + m * 2048 + k * 1024); } while (0)
; #define PG8_MMA(ai, bj, At, Bt) do { __builtin_amdgcn_s_setprio(1); _Pragma("unroll") for (int m = 0; m < 4; ++m) _Pragma("unroll") for (int n = 0; n < 2; ++n) _Pragma("unroll") for (int k = 0; k < 2; ++k) \
;         acc[ai][bj][m][n] = __builtin_amdgcn_mfma_f32_16x16x32_bf16(Bt[n][k], At[m][k], acc[ai][bj][m][n], 0, 0, 0); __builtin_amdgcn_s_setprio(0); } while (0)
; #define PG8_WAIT_V(n) asm volatile("s_waitcnt vmcnt(" #n ")" ::: "memory")
; #define PG8_WAIT_L(n) asm volatile("s_waitcnt lgkmcnt(" #n ")" ::: "memory")
; #define PG8_BAR __builtin_amdgcn_s_barrier()
; #define PG8_SCHED __builtin_amdgcn_sched_barrier(0)
;     __device__ __forceinline__ void operator()(const f32x4 (&acc)[2][2][4][2], const Unit& u, int wr, int wc, int fr, int fq) const {
;         asm volatile("" : "+v"(fr), "+v"(fq));
;         const int br = u.pm >> 6, pm = u.pm & 63, pn = u.pn & 7;
;         const int row0 = pm * BM + wr * 64 + fr, col0 = pn * BM + wc * 32 + 8 * fq;
; #pragma unroll
;         for (int ai = 0; ai < 2; ++ai) {
;             u32x4 gv[4][2]; unsigned long long q0[4][2], q1[4][2];
; #pragma unroll
;             for (int m = 0; m < 4; ++m)
; #pragma unroll
;                 for (int bj = 0; bj < 2; ++bj) { const int row = row0 + ai * HALF + m * 16, col = col0 + bj * HALF;
;                     gv[m][bj] = *(const u32x4*)(G + (size_t)row * NGATE + br * 2048 + col);
; template <class Epi, class Sched, bool ALIGN_EPI = false, bool SP2 = false>
; __device__ __forceinline__ void gemm_phase(PG8_LAS unsigned char* lds, const Gemm g, const Sched& S, const Epi& E, const int tid_in) {
;     ...
;             PG8_LDA(At, 1, 1); PG8_STAGE(PG8_SB(1, 0), b3, voffB); PG8_STAGE(PG8_SB(1, 1), b3 + hstep, voffB); PG8_STAGE(PG8_SA(1, 0), a3, voffA);
;             PG8_WAIT_V(8); PG8_WAIT_L(0); PG8_BAR; PG8_MMA(1, 0, At, B0); PG8_MMA(1, 1, At, B1); PG8_BAR; PG8_SCHED;
	s_add_i32 s31, s31, s52
	v_lshl_add_u64 v[218:219], v[218:219], 0, s[64:65]
	s_mov_b32 m0, s31
	ds_read_b128 v[186:189], v241 offset:49152
	ds_read_b128 v[190:193], v241 offset:50176
	ds_read_b128 v[194:197], v241 offset:51200
	ds_read_b128 v[198:201], v241 offset:52224
	ds_read_b128 v[202:205], v241 offset:53248
	ds_read_b128 v[206:209], v241 offset:54272
	ds_read_b128 v[210:213], v241 offset:55296
	ds_read_b128 v[214:217], v241 offset:56320
	global_load_lds_dwordx4 v[218:219], off
	s_add_i32 m0, s31, 0x2000
	s_add_u32 s46, s46, 0x20080
	v_lshl_add_u64 v[218:219], v[220:221], 0, s[64:65]
	s_addc_u32 s47, s47, 0
	s_add_i32 s31, s89, s52
	global_load_lds_dwordx4 v[218:219], off
	v_lshl_add_u64 v[218:219], s[46:47], 0, v[0:1]
	s_mov_b32 m0, s31
	s_nop 0
	global_load_lds_dwordx4 v[218:219], off
	v_lshl_add_u64 v[218:219], s[46:47], 0, v[180:181]
	s_add_i32 m0, s31, 0x2000
	s_nop 0
	global_load_lds_dwordx4 v[218:219], off
	v_lshl_add_u64 v[218:219], v[222:223], 0, s[64:65]
	s_mov_b32 m0, s83
	s_nop 0
	global_load_lds_dwordx4 v[218:219], off
	v_lshl_add_u64 v[218:219], v[224:225], 0, s[64:65]
	s_mov_b32 m0, s84
	s_nop 0
	global_load_lds_dwordx4 v[218:219], off
	s_waitcnt vmcnt(8)
	s_waitcnt lgkmcnt(0)
	s_barrier
	s_setprio 1
	s_waitcnt lgkmcnt(0)
	v_mfma_f32_16x16x32_bf16 v[62:65], v[130:133], v[186:189], v[62:65]
	v_mfma_f32_16x16x32_bf16 v[58:61], v[138:141], v[186:189], v[58:61]
	v_mfma_f32_16x16x32_bf16 v[46:49], v[130:133], v[194:197], v[46:49]
	v_mfma_f32_16x16x32_bf16 v[42:45], v[138:141], v[194:197], v[42:45]
	v_mfma_f32_16x16x32_bf16 v[30:33], v[130:133], v[202:205], v[30:33]
	v_mfma_f32_16x16x32_bf16 v[26:29], v[138:141], v[202:205], v[26:29]
	v_mfma_f32_16x16x32_bf16 v[14:17], v[130:133], v[210:213], v[14:17]
	v_mfma_f32_16x16x32_bf16 v[10:13], v[138:141], v[210:213], v[10:13]
	v_mfma_f32_16x16x32_bf16 v[62:65], v[134:137], v[190:193], v[62:65]
	v_mfma_f32_16x16x32_bf16 v[58:61], v[142:145], v[190:193], v[58:61]
	v_mfma_f32_16x16x32_bf16 v[46:49], v[134:137], v[198:201], v[46:49]
	v_mfma_f32_16x16x32_bf16 v[42:45], v[142:145], v[198:201], v[42:45]
	v_mfma_f32_16x16x32_bf16 v[30:33], v[134:137], v[206:209], v[30:33]
	v_mfma_f32_16x16x32_bf16 v[26:29], v[142:145], v[206:209], v[26:29]
	v_mfma_f32_16x16x32_bf16 v[14:17], v[134:137], v[214:217], v[14:17]
	v_mfma_f32_16x16x32_bf16 v[10:13], v[142:145], v[214:217], v[10:13]
	s_setprio 0
	s_setprio 1
	v_mfma_f32_16x16x32_bf16 v[54:57], v[146:149], v[186:189], v[54:57]
	v_mfma_f32_16x16x32_bf16 v[50:53], v[154:157], v[186:189], v[50:53]
	v_mfma_f32_16x16x32_bf16 v[38:41], v[146:149], v[194:197], v[38:41]
	v_mfma_f32_16x16x32_bf16 v[34:37], v[154:157], v[194:197], v[34:37]
	v_mfma_f32_16x16x32_bf16 v[22:25], v[146:149], v[202:205], v[22:25]
	v_mfma_f32_16x16x32_bf16 v[18:21], v[154:157], v[202:205], v[18:21]
	v_mfma_f32_16x16x32_bf16 v[6:9], v[146:149], v[210:213], v[6:9]
	v_mfma_f32_16x16x32_bf16 v[2:5], v[154:157], v[210:213], v[2:5]
	v_mfma_f32_16x16x32_bf16 v[54:57], v[150:153], v[190:193], v[54:57]
	v_mfma_f32_16x16x32_bf16 v[50:53], v[158:161], v[190:193], v[50:53]
	v_mfma_f32_16x16x32_bf16 v[38:41], v[150:153], v[198:201], v[38:41]
	v_mfma_f32_16x16x32_bf16 v[34:37], v[158:161], v[198:201], v[34:37]
	v_mfma_f32_16x16x32_bf16 v[22:25], v[150:153], v[206:209], v[22:25]
	v_mfma_f32_16x16x32_bf16 v[18:21], v[158:161], v[206:209], v[18:21]
	v_mfma_f32_16x16x32_bf16 v[6:9], v[150:153], v[214:217], v[6:9]
	v_mfma_f32_16x16x32_bf16 v[2:5], v[158:161], v[214:217], v[2:5]
	s_setprio 0
	s_barrier
	s_add_i32 s88, s88, 2
	s_add_u32 s44, s44, 0x100
	s_addc_u32 s45, s45, 0
	s_add_u32 s72, s72, 0x100
	s_addc_u32 s87, s87, 0
	s_cmp_gt_u32 s88, 5
	s_cbranch_scc0 .LBB0_86
	s_and_b64 vcc, exec, s[16:17]
	s_cbranch_vccz .LBB0_89
	s_barrier
.LBB0_89:
	s_lshl_b32 s8, s8, 8
	s_lshl_b32 s9, s42, 8
	s_and_b32 s8, s8, 0x700
	v_mov_b32_e32 v130, v171
	v_mov_b32_e32 v131, v239
	s_ashr_i32 s27, s42, 6
	s_and_b32 s9, s9, 0x3f00
	s_or_b32 s8, s8, s73
	s_add_i32 s9, s9, s67
	v_lshl_add_u32 v218, v131, 3, s8
	s_lshl_b32 s8, s27, 11
	v_add_u32_e32 v220, s9, v130
	s_ashr_i32 s9, s8, 31
	s_cmp_gt_i32 s27, 0
	s_cselect_b64 s[44:45], -1, 0
	s_lshl_b64 s[8:9], s[8:9], 1
	s_add_u32 s42, s63, s8
	s_addc_u32 s43, s66, s9
	v_mov_b64_e32 v[130:131], s[42:43]
	s_movk_i32 s8, 0x3000
	v_mad_i64_i32 v[130:131], s[8:9], v220, s8, v[130:131]
	v_ashrrev_i32_e32 v219, 31, v218
	v_lshl_add_u64 v[130:131], v[218:219], 1, v[130:131]
	v_ashrrev_i32_e32 v221, 31, v220
	v_lshlrev_b64 v[226:227], 12, v[220:221]
	v_lshl_add_u64 v[226:227], s[14:15], 0, v[226:227]
	v_lshl_add_u64 v[226:227], v[218:219], 1, v[226:227]
	v_mov_b32_e32 v222, v130
	v_mov_b32_e32 v223, v131
	v_mov_b32_e32 v228, 0x1000
	v_mov_b32_e32 v229, 0
	v_lshl_add_u64 v[224:225], v[222:223], 0, v[228:229]
	s_mov_b32 s8, 0x30000
	s_mov_b32 s9, 0
	s_mov_b32 s46, 0x10000
	s_mov_b32 s47, 0
	s_mov_b32 s44, 0xf0000
	s_mov_b32 s45, 0
	s_mov_b32 s42, 0x50000
	s_mov_b32 s43, 0
	s_cmp_eq_u32 s27, 2
	s_cbranch_scc1 .Lrb_final
; __device__ __forceinline__ float bf_lo(unsigned w) { return __uint_as_float(w << 16); }
; __device__ __forceinline__ float bf_hi(unsigned w) { return __uint_as_float(w & 0xffff0000u); }
;     __device__ __forceinline__ void operator()(const f32x4 (&acc)[2][2][4][2], const Unit& u, int wr, int wc, int fr, int fq) const {
;     ...
;                 for (int bj = 0; bj < 2; ++bj) { const int row = row0 + ai * HALF + m * 16, col = col0 + bj * HALF;
;                     gv[m][bj] = *(const u32x4*)(G + (size_t)row * NGATE + br * 2048 + col);
;                     if (br > 0) { bf16_t* mp = Mg + (size_t)row * DM + col;
;                         q0[m][bj] = __hip_atomic_load((unsigned long long*)mp, __ATOMIC_RELAXED, __HIP_MEMORY_SCOPE_AGENT);
;                         q1[m][bj] = __hip_atomic_load((unsigned long long*)mp + 1, __ATOMIC_RELAXED, __HIP_MEMORY_SCOPE_AGENT); } }
; #pragma unroll
;             for (int m = 0; m < 4; ++m)
; #pragma unroll
;                 for (int bj = 0; bj < 2; ++bj) { const int row = row0 + ai * HALF + m * 16, col = col0 + bj * HALF; const u32x4 g4 = gv[m][bj];
;                     const f32x4 a0 = acc[ai][bj][m][0], a1 = acc[ai][bj][m][1];
;                     float f0 = a0[0] * bf_lo(g4.x), f1 = a0[1] * bf_hi(g4.x), f2 = a0[2] * bf_lo(g4.y), f3 = a0[3] * bf_hi(g4.y);
;                     float f4 = a1[0] * bf_lo(g4.z), f5 = a1[1] * bf_hi(g4.z), f6 = a1[2] * bf_lo(g4.w), f7 = a1[3] * bf_hi(g4.w);
;                     if (br > 0) {
;                         const unsigned p0 = (unsigned)q0[m][bj], p1 = (unsigned)(q0[m][bj] >> 32), p2 = (unsigned)q1[m][bj], p3 = (unsigned)(q1[m][bj] >> 32);
;                         f0 += bf_lo(p0); f1 += bf_hi(p0); f2 += bf_lo(p1); f3 += bf_hi(p1); f4 += bf_lo(p2); f5 += bf_hi(p2); f6 += bf_lo(p3); f7 += bf_hi(p3);
	global_load_dwordx4 v[130:133], v[222:223], off
	global_load_dwordx4 v[186:189], v[224:225], off
	global_load_dwordx4 v[134:137], v[222:223], off offset:256
	global_load_dwordx4 v[190:193], v[224:225], off offset:256
	v_lshl_add_u64 v[222:223], v[222:223], 0, s[8:9]
	v_lshl_add_u64 v[224:225], v[224:225], 0, s[8:9]
	global_load_dwordx4 v[138:141], v[222:223], off
	global_load_dwordx4 v[194:197], v[224:225], off
	global_load_dwordx4 v[142:145], v[222:223], off offset:256
	global_load_dwordx4 v[198:201], v[224:225], off offset:256
	v_lshl_add_u64 v[222:223], v[222:223], 0, s[8:9]
	v_lshl_add_u64 v[224:225], v[224:225], 0, s[8:9]
	global_load_dwordx4 v[146:149], v[222:223], off
	global_load_dwordx4 v[202:205], v[224:225], off
	global_load_dwordx4 v[150:153], v[222:223], off offset:256
	global_load_dwordx4 v[206:209], v[224:225], off offset:256
	v_lshl_add_u64 v[222:223], v[222:223], 0, s[8:9]
	v_lshl_add_u64 v[224:225], v[224:225], 0, s[8:9]
	global_load_dwordx4 v[154:157], v[222:223], off
	global_load_dwordx4 v[210:213], v[224:225], off
	global_load_dwordx4 v[158:161], v[222:223], off offset:256
	global_load_dwordx4 v[214:217], v[224:225], off offset:256
	s_waitcnt vmcnt(0)
	v_lshlrev_b32_e32 v218, 16, v130
	v_and_b32_e32 v219, 0xffff0000, v130
	v_lshlrev_b32_e32 v220, 16, v186
	v_and_b32_e32 v221, 0xffff0000, v186
	v_max_f32_e32 v220, 0x21800000, v220
	v_max_f32_e32 v221, 0x21800000, v221
	v_max_f32_e32 v218, 0x21800000, v218
	v_max_f32_e32 v219, 0x21800000, v219
	v_rcp_f32_e32 v220, v220
	v_rcp_f32_e32 v221, v221
	v_mul_f32_e32 v218, v218, v220
	v_mul_f32_e32 v219, v219, v221
	v_pk_mul_f32 v[126:127], v[126:127], v[218:219]
	v_lshlrev_b32_e32 v228, 16, v131
	v_and_b32_e32 v229, 0xffff0000, v131
	v_lshlrev_b32_e32 v242, 16, v187
	v_and_b32_e32 v243, 0xffff0000, v187
	v_max_f32_e32 v242, 0x21800000, v242
	v_max_f32_e32 v243, 0x21800000, v243
	v_max_f32_e32 v228, 0x21800000, v228
	v_max_f32_e32 v229, 0x21800000, v229
	v_rcp_f32_e32 v242, v242
	v_rcp_f32_e32 v243, v243
	v_mul_f32_e32 v228, v228, v242
	v_mul_f32_e32 v229, v229, v243
	v_pk_mul_f32 v[128:129], v[128:129], v[228:229]
	v_lshlrev_b32_e32 v218, 16, v132
	v_and_b32_e32 v219, 0xffff0000, v132
	v_lshlrev_b32_e32 v220, 16, v188
	v_and_b32_e32 v221, 0xffff0000, v188
	v_max_f32_e32 v220, 0x21800000, v220
	v_max_f32_e32 v221, 0x21800000, v221
	v_max_f32_e32 v218, 0x21800000, v218
	v_max_f32_e32 v219, 0x21800000, v219
	v_rcp_f32_e32 v220, v220
	v_rcp_f32_e32 v221, v221
	v_mul_f32_e32 v218, v218, v220
	v_mul_f32_e32 v219, v219, v221
	v_pk_mul_f32 v[122:123], v[122:123], v[218:219]
	v_lshlrev_b32_e32 v228, 16, v133
	v_and_b32_e32 v229, 0xffff0000, v133
	v_lshlrev_b32_e32 v242, 16, v189
	v_and_b32_e32 v243, 0xffff0000, v189
	v_max_f32_e32 v242, 0x21800000, v242
	v_max_f32_e32 v243, 0x21800000, v243
	v_max_f32_e32 v228, 0x21800000, v228
	v_max_f32_e32 v229, 0x21800000, v229
	v_rcp_f32_e32 v242, v242
	v_rcp_f32_e32 v243, v243
	v_mul_f32_e32 v228, v228, v242
	v_mul_f32_e32 v229, v229, v243
	v_pk_mul_f32 v[124:125], v[124:125], v[228:229]
	v_lshlrev_b32_e32 v218, 16, v134
	v_and_b32_e32 v219, 0xffff0000, v134
	v_lshlrev_b32_e32 v220, 16, v190
	v_and_b32_e32 v221, 0xffff0000, v190
	v_max_f32_e32 v220, 0x21800000, v220
	v_max_f32_e32 v221, 0x21800000, v221
	v_max_f32_e32 v218, 0x21800000, v218
	v_max_f32_e32 v219, 0x21800000, v219
	v_rcp_f32_e32 v220, v220
	v_rcp_f32_e32 v221, v221
	v_mul_f32_e32 v218, v218, v220
	v_mul_f32_e32 v219, v219, v221
	v_pk_mul_f32 v[118:119], v[118:119], v[218:219]
	v_lshlrev_b32_e32 v228, 16, v135
	v_and_b32_e32 v229, 0xffff0000, v135
	v_lshlrev_b32_e32 v242, 16, v191
	v_and_b32_e32 v243, 0xffff0000, v191
	v_max_f32_e32 v242, 0x21800000, v242
	v_max_f32_e32 v243, 0x21800000, v243
	v_max_f32_e32 v228, 0x21800000, v228
	v_max_f32_e32 v229, 0x21800000, v229
	v_rcp_f32_e32 v242, v242
	v_rcp_f32_e32 v243, v243
	v_mul_f32_e32 v228, v228, v242
	v_mul_f32_e32 v229, v229, v243
	v_pk_mul_f32 v[120:121], v[120:121], v[228:229]
	v_lshlrev_b32_e32 v218, 16, v136
	v_and_b32_e32 v219, 0xffff0000, v136
	v_lshlrev_b32_e32 v220, 16, v192
	v_and_b32_e32 v221, 0xffff0000, v192
	v_max_f32_e32 v220, 0x21800000, v220
	v_max_f32_e32 v221, 0x21800000, v221
	v_max_f32_e32 v218, 0x21800000, v218
	v_max_f32_e32 v219, 0x21800000, v219
	v_rcp_f32_e32 v220, v220
	v_rcp_f32_e32 v221, v221
	v_mul_f32_e32 v218, v218, v220
	v_mul_f32_e32 v219, v219, v221
	v_pk_mul_f32 v[114:115], v[114:115], v[218:219]
	v_lshlrev_b32_e32 v228, 16, v137
	v_and_b32_e32 v229, 0xffff0000, v137
	v_lshlrev_b32_e32 v242, 16, v193
	v_and_b32_e32 v243, 0xffff0000, v193
	v_max_f32_e32 v242, 0x21800000, v242
	v_max_f32_e32 v243, 0x21800000, v243
	v_max_f32_e32 v228, 0x21800000, v228
	v_max_f32_e32 v229, 0x21800000, v229
	v_rcp_f32_e32 v242, v242
	v_rcp_f32_e32 v243, v243
	v_mul_f32_e32 v228, v228, v242
	v_mul_f32_e32 v229, v229, v243
	v_pk_mul_f32 v[116:117], v[116:117], v[228:229]
	v_lshlrev_b32_e32 v218, 16, v138
	v_and_b32_e32 v219, 0xffff0000, v138
	v_lshlrev_b32_e32 v220, 16, v194
	v_and_b32_e32 v221, 0xffff0000, v194
	v_max_f32_e32 v220, 0x21800000, v220
	v_max_f32_e32 v221, 0x21800000, v221
	v_max_f32_e32 v218, 0x21800000, v218
	v_max_f32_e32 v219, 0x21800000, v219
	v_rcp_f32_e32 v220, v220
	v_rcp_f32_e32 v221, v221
	v_mul_f32_e32 v218, v218, v220
	v_mul_f32_e32 v219, v219, v221
	v_pk_mul_f32 v[110:111], v[110:111], v[218:219]
	v_lshlrev_b32_e32 v228, 16, v139
	v_and_b32_e32 v229, 0xffff0000, v139
	v_lshlrev_b32_e32 v242, 16, v195
	v_and_b32_e32 v243, 0xffff0000, v195
	v_max_f32_e32 v242, 0x21800000, v242
	v_max_f32_e32 v243, 0x21800000, v243
	v_max_f32_e32 v228, 0x21800000, v228
	v_max_f32_e32 v229, 0x21800000, v229
; __device__ __forceinline__ float bf_lo(unsigned w) { return __uint_as_float(w << 16); }
; __device__ __forceinline__ float bf_hi(unsigned w) { return __uint_as_float(w & 0xffff0000u); }
;     __device__ __forceinline__ void operator()(const f32x4 (&acc)[2][2][4][2], const Unit& u, int wr, int wc, int fr, int fq) const {
;     ...
;                 for (int bj = 0; bj < 2; ++bj) { const int row = row0 + ai * HALF + m * 16, col = col0 + bj * HALF;
;                     gv[m][bj] = *(const u32x4*)(G + (size_t)row * NGATE + br * 2048 + col);
;                     if (br > 0) { bf16_t* mp = Mg + (size_t)row * DM + col;
;                         q0[m][bj] = __hip_atomic_load((unsigned long long*)mp, __ATOMIC_RELAXED, __HIP_MEMORY_SCOPE_AGENT);
;                         q1[m][bj] = __hip_atomic_load((unsigned long long*)mp + 1, __ATOMIC_RELAXED, __HIP_MEMORY_SCOPE_AGENT); } }
; #pragma unroll
;             for (int m = 0; m < 4; ++m)
; #pragma unroll
;                 for (int bj = 0; bj < 2; ++bj) { const int row = row0 + ai * HALF + m * 16, col = col0 + bj * HALF; const u32x4 g4 = gv[m][bj];
;                     const f32x4 a0 = acc[ai][bj][m][0], a1 = acc[ai][bj][m][1];
;                     float f0 = a0[0] * bf_lo(g4.x), f1 = a0[1] * bf_hi(g4.x), f2 = a0[2] * bf_lo(g4.y), f3 = a0[3] * bf_hi(g4.y);
;                     float f4 = a1[0] * bf_lo(g4.z), f5 = a1[1] * bf_hi(g4.z), f6 = a1[2] * bf_lo(g4.w), f7 = a1[3] * bf_hi(g4.w);
;                     if (br > 0) {
;                         const unsigned p0 = (unsigned)q0[m][bj], p1 = (unsigned)(q0[m][bj] >> 32), p2 = (unsigned)q1[m][bj], p3 = (unsigned)(q1[m][bj] >> 32);
;                         f0 += bf_lo(p0); f1 += bf_hi(p0); f2 += bf_lo(p1); f3 += bf_hi(p1); f4 += bf_lo(p2); f5 += bf_hi(p2); f6 += bf_lo(p3); f7 += bf_hi(p3);
	v_rcp_f32_e32 v242, v242
	v_rcp_f32_e32 v243, v243
	v_mul_f32_e32 v228, v228, v242
	v_mul_f32_e32 v229, v229, v243
	v_pk_mul_f32 v[112:113], v[112:113], v[228:229]
	v_lshlrev_b32_e32 v218, 16, v140
	v_and_b32_e32 v219, 0xffff0000, v140
	v_lshlrev_b32_e32 v220, 16, v196
	v_and_b32_e32 v221, 0xffff0000, v196
	v_max_f32_e32 v220, 0x21800000, v220
	v_max_f32_e32 v221, 0x21800000, v221
	v_max_f32_e32 v218, 0x21800000, v218
	v_max_f32_e32 v219, 0x21800000, v219
	v_rcp_f32_e32 v220, v220
	v_rcp_f32_e32 v221, v221
	v_mul_f32_e32 v218, v218, v220
	v_mul_f32_e32 v219, v219, v221
	v_pk_mul_f32 v[106:107], v[106:107], v[218:219]
	v_lshlrev_b32_e32 v228, 16, v141
	v_and_b32_e32 v229, 0xffff0000, v141
	v_lshlrev_b32_e32 v242, 16, v197
	v_and_b32_e32 v243, 0xffff0000, v197
	v_max_f32_e32 v242, 0x21800000, v242
	v_max_f32_e32 v243, 0x21800000, v243
	v_max_f32_e32 v228, 0x21800000, v228
	v_max_f32_e32 v229, 0x21800000, v229
	v_rcp_f32_e32 v242, v242
	v_rcp_f32_e32 v243, v243
	v_mul_f32_e32 v228, v228, v242
	v_mul_f32_e32 v229, v229, v243
	v_pk_mul_f32 v[108:109], v[108:109], v[228:229]
	v_lshlrev_b32_e32 v218, 16, v142
	v_and_b32_e32 v219, 0xffff0000, v142
	v_lshlrev_b32_e32 v220, 16, v198
	v_and_b32_e32 v221, 0xffff0000, v198
	v_max_f32_e32 v220, 0x21800000, v220
	v_max_f32_e32 v221, 0x21800000, v221
	v_max_f32_e32 v218, 0x21800000, v218
	v_max_f32_e32 v219, 0x21800000, v219
	v_rcp_f32_e32 v220, v220
	v_rcp_f32_e32 v221, v221
	v_mul_f32_e32 v218, v218, v220
	v_mul_f32_e32 v219, v219, v221
	v_pk_mul_f32 v[102:103], v[102:103], v[218:219]
	v_lshlrev_b32_e32 v228, 16, v143
	v_and_b32_e32 v229, 0xffff0000, v143
	v_lshlrev_b32_e32 v242, 16, v199
	v_and_b32_e32 v243, 0xffff0000, v199
	v_max_f32_e32 v242, 0x21800000, v242
	v_max_f32_e32 v243, 0x21800000, v243
	v_max_f32_e32 v228, 0x21800000, v228
	v_max_f32_e32 v229, 0x21800000, v229
	v_rcp_f32_e32 v242, v242
	v_rcp_f32_e32 v243, v243
	v_mul_f32_e32 v228, v228, v242
	v_mul_f32_e32 v229, v229, v243
	v_pk_mul_f32 v[104:105], v[104:105], v[228:229]
	v_lshlrev_b32_e32 v218, 16, v144
	v_and_b32_e32 v219, 0xffff0000, v144
	v_lshlrev_b32_e32 v220, 16, v200
	v_and_b32_e32 v221, 0xffff0000, v200
	v_max_f32_e32 v220, 0x21800000, v220
	v_max_f32_e32 v221, 0x21800000, v221
	v_max_f32_e32 v218, 0x21800000, v218
	v_max_f32_e32 v219, 0x21800000, v219
	v_rcp_f32_e32 v220, v220
	v_rcp_f32_e32 v221, v221
	v_mul_f32_e32 v218, v218, v220
	v_mul_f32_e32 v219, v219, v221
	v_pk_mul_f32 v[98:99], v[98:99], v[218:219]
	v_lshlrev_b32_e32 v228, 16, v145
	v_and_b32_e32 v229, 0xffff0000, v145
	v_lshlrev_b32_e32 v242, 16, v201
	v_and_b32_e32 v243, 0xffff0000, v201
	v_max_f32_e32 v242, 0x21800000, v242
	v_max_f32_e32 v243, 0x21800000, v243
	v_max_f32_e32 v228, 0x21800000, v228
	v_max_f32_e32 v229, 0x21800000, v229
	v_rcp_f32_e32 v242, v242
	v_rcp_f32_e32 v243, v243
	v_mul_f32_e32 v228, v228, v242
	v_mul_f32_e32 v229, v229, v243
	v_pk_mul_f32 v[100:101], v[100:101], v[228:229]
	v_lshlrev_b32_e32 v218, 16, v146
	v_and_b32_e32 v219, 0xffff0000, v146
	v_lshlrev_b32_e32 v220, 16, v202
	v_and_b32_e32 v221, 0xffff0000, v202
	v_max_f32_e32 v220, 0x21800000, v220
	v_max_f32_e32 v221, 0x21800000, v221
	v_max_f32_e32 v218, 0x21800000, v218
	v_max_f32_e32 v219, 0x21800000, v219
	v_rcp_f32_e32 v220, v220
	v_rcp_f32_e32 v221, v221
	v_mul_f32_e32 v218, v218, v220
	v_mul_f32_e32 v219, v219, v221
	v_pk_mul_f32 v[94:95], v[94:95], v[218:219]
	v_lshlrev_b32_e32 v228, 16, v147
	v_and_b32_e32 v229, 0xffff0000, v147
	v_lshlrev_b32_e32 v242, 16, v203
	v_and_b32_e32 v243, 0xffff0000, v203
	v_max_f32_e32 v242, 0x21800000, v242
	v_max_f32_e32 v243, 0x21800000, v243
	v_max_f32_e32 v228, 0x21800000, v228
	v_max_f32_e32 v229, 0x21800000, v229
	v_rcp_f32_e32 v242, v242
	v_rcp_f32_e32 v243, v243
	v_mul_f32_e32 v228, v228, v242
	v_mul_f32_e32 v229, v229, v243
	v_pk_mul_f32 v[96:97], v[96:97], v[228:229]
	v_lshlrev_b32_e32 v218, 16, v148
	v_and_b32_e32 v219, 0xffff0000, v148
	v_lshlrev_b32_e32 v220, 16, v204
	v_and_b32_e32 v221, 0xffff0000, v204
	v_max_f32_e32 v220, 0x21800000, v220
	v_max_f32_e32 v221, 0x21800000, v221
	v_max_f32_e32 v218, 0x21800000, v218
	v_max_f32_e32 v219, 0x21800000, v219
	v_rcp_f32_e32 v220, v220
	v_rcp_f32_e32 v221, v221
	v_mul_f32_e32 v218, v218, v220
	v_mul_f32_e32 v219, v219, v221
	v_pk_mul_f32 v[90:91], v[90:91], v[218:219]
	v_lshlrev_b32_e32 v228, 16, v149
	v_and_b32_e32 v229, 0xffff0000, v149
	v_lshlrev_b32_e32 v242, 16, v205
	v_and_b32_e32 v243, 0xffff0000, v205
	v_max_f32_e32 v242, 0x21800000, v242
	v_max_f32_e32 v243, 0x21800000, v243
	v_max_f32_e32 v228, 0x21800000, v228
	v_max_f32_e32 v229, 0x21800000, v229
	v_rcp_f32_e32 v242, v242
	v_rcp_f32_e32 v243, v243
	v_mul_f32_e32 v228, v228, v242
	v_mul_f32_e32 v229, v229, v243
	v_pk_mul_f32 v[92:93], v[92:93], v[228:229]
	v_lshlrev_b32_e32 v218, 16, v150
	v_and_b32_e32 v219, 0xffff0000, v150
	v_lshlrev_b32_e32 v220, 16, v206
	v_and_b32_e32 v221, 0xffff0000, v206
	v_max_f32_e32 v220, 0x21800000, v220
	v_max_f32_e32 v221, 0x21800000, v221
	v_max_f32_e32 v218, 0x21800000, v218
	v_max_f32_e32 v219, 0x21800000, v219
	v_rcp_f32_e32 v220, v220
	v_rcp_f32_e32 v221, v221
	v_mul_f32_e32 v218, v218, v220
	v_mul_f32_e32 v219, v219, v221
	v_pk_mul_f32 v[86:87], v[86:87], v[218:219]
	v_lshlrev_b32_e32 v228, 16, v151
	v_and_b32_e32 v229, 0xffff0000, v151
	v_lshlrev_b32_e32 v242, 16, v207
	v_and_b32_e32 v243, 0xffff0000, v207
	v_max_f32_e32 v242, 0x21800000, v242
	v_max_f32_e32 v243, 0x21800000, v243
	v_max_f32_e32 v228, 0x21800000, v228
	v_max_f32_e32 v229, 0x21800000, v229
	v_rcp_f32_e32 v242, v242
	v_rcp_f32_e32 v243, v243
	v_mul_f32_e32 v228, v228, v242
	v_mul_f32_e32 v229, v229, v243
; __device__ __forceinline__ float bf_lo(unsigned w) { return __uint_as_float(w << 16); }
; __device__ __forceinline__ float bf_hi(unsigned w) { return __uint_as_float(w & 0xffff0000u); }
;     __device__ __forceinline__ void operator()(const f32x4 (&acc)[2][2][4][2], const Unit& u, int wr, int wc, int fr, int fq) const {
;     ...
;                 for (int bj = 0; bj < 2; ++bj) { const int row = row0 + ai * HALF + m * 16, col = col0 + bj * HALF;
;                     gv[m][bj] = *(const u32x4*)(G + (size_t)row * NGATE + br * 2048 + col);
;                     if (br > 0) { bf16_t* mp = Mg + (size_t)row * DM + col;
;                         q0[m][bj] = __hip_atomic_load((unsigned long long*)mp, __ATOMIC_RELAXED, __HIP_MEMORY_SCOPE_AGENT);
;                         q1[m][bj] = __hip_atomic_load((unsigned long long*)mp + 1, __ATOMIC_RELAXED, __HIP_MEMORY_SCOPE_AGENT); } }
; #pragma unroll
;             for (int m = 0; m < 4; ++m)
; #pragma unroll
;                 for (int bj = 0; bj < 2; ++bj) { const int row = row0 + ai * HALF + m * 16, col = col0 + bj * HALF; const u32x4 g4 = gv[m][bj];
;                     const f32x4 a0 = acc[ai][bj][m][0], a1 = acc[ai][bj][m][1];
;                     float f0 = a0[0] * bf_lo(g4.x), f1 = a0[1] * bf_hi(g4.x), f2 = a0[2] * bf_lo(g4.y), f3 = a0[3] * bf_hi(g4.y);
;                     float f4 = a1[0] * bf_lo(g4.z), f5 = a1[1] * bf_hi(g4.z), f6 = a1[2] * bf_lo(g4.w), f7 = a1[3] * bf_hi(g4.w);
;                     if (br > 0) {
;                         const unsigned p0 = (unsigned)q0[m][bj], p1 = (unsigned)(q0[m][bj] >> 32), p2 = (unsigned)q1[m][bj], p3 = (unsigned)(q1[m][bj] >> 32);
;                         f0 += bf_lo(p0); f1 += bf_hi(p0); f2 += bf_lo(p1); f3 += bf_hi(p1); f4 += bf_lo(p2); f5 += bf_hi(p2); f6 += bf_lo(p3); f7 += bf_hi(p3);
	v_pk_mul_f32 v[88:89], v[88:89], v[228:229]
	v_lshlrev_b32_e32 v218, 16, v152
	v_and_b32_e32 v219, 0xffff0000, v152
	v_lshlrev_b32_e32 v220, 16, v208
	v_and_b32_e32 v221, 0xffff0000, v208
	v_max_f32_e32 v220, 0x21800000, v220
	v_max_f32_e32 v221, 0x21800000, v221
	v_max_f32_e32 v218, 0x21800000, v218
	v_max_f32_e32 v219, 0x21800000, v219
	v_rcp_f32_e32 v220, v220
	v_rcp_f32_e32 v221, v221
	v_mul_f32_e32 v218, v218, v220
	v_mul_f32_e32 v219, v219, v221
	v_pk_mul_f32 v[82:83], v[82:83], v[218:219]
	v_lshlrev_b32_e32 v228, 16, v153
	v_and_b32_e32 v229, 0xffff0000, v153
	v_lshlrev_b32_e32 v242, 16, v209
	v_and_b32_e32 v243, 0xffff0000, v209
	v_max_f32_e32 v242, 0x21800000, v242
	v_max_f32_e32 v243, 0x21800000, v243
	v_max_f32_e32 v228, 0x21800000, v228
	v_max_f32_e32 v229, 0x21800000, v229
	v_rcp_f32_e32 v242, v242
	v_rcp_f32_e32 v243, v243
	v_mul_f32_e32 v228, v228, v242
	v_mul_f32_e32 v229, v229, v243
	v_pk_mul_f32 v[84:85], v[84:85], v[228:229]
	v_lshlrev_b32_e32 v218, 16, v154
	v_and_b32_e32 v219, 0xffff0000, v154
	v_lshlrev_b32_e32 v220, 16, v210
	v_and_b32_e32 v221, 0xffff0000, v210
	v_max_f32_e32 v220, 0x21800000, v220
	v_max_f32_e32 v221, 0x21800000, v221
	v_max_f32_e32 v218, 0x21800000, v218
	v_max_f32_e32 v219, 0x21800000, v219
	v_rcp_f32_e32 v220, v220
	v_rcp_f32_e32 v221, v221
	v_mul_f32_e32 v218, v218, v220
	v_mul_f32_e32 v219, v219, v221
	v_pk_mul_f32 v[78:79], v[78:79], v[218:219]
	v_lshlrev_b32_e32 v228, 16, v155
	v_and_b32_e32 v229, 0xffff0000, v155
	v_lshlrev_b32_e32 v242, 16, v211
	v_and_b32_e32 v243, 0xffff0000, v211
	v_max_f32_e32 v242, 0x21800000, v242
	v_max_f32_e32 v243, 0x21800000, v243
	v_max_f32_e32 v228, 0x21800000, v228
	v_max_f32_e32 v229, 0x21800000, v229
	v_rcp_f32_e32 v242, v242
	v_rcp_f32_e32 v243, v243
	v_mul_f32_e32 v228, v228, v242
	v_mul_f32_e32 v229, v229, v243
	v_pk_mul_f32 v[80:81], v[80:81], v[228:229]
	v_lshlrev_b32_e32 v218, 16, v156
	v_and_b32_e32 v219, 0xffff0000, v156
	v_lshlrev_b32_e32 v220, 16, v212
	v_and_b32_e32 v221, 0xffff0000, v212
	v_max_f32_e32 v220, 0x21800000, v220
	v_max_f32_e32 v221, 0x21800000, v221
	v_max_f32_e32 v218, 0x21800000, v218
	v_max_f32_e32 v219, 0x21800000, v219
	v_rcp_f32_e32 v220, v220
	v_rcp_f32_e32 v221, v221
	v_mul_f32_e32 v218, v218, v220
	v_mul_f32_e32 v219, v219, v221
	v_pk_mul_f32 v[74:75], v[74:75], v[218:219]
	v_lshlrev_b32_e32 v228, 16, v157
	v_and_b32_e32 v229, 0xffff0000, v157
	v_lshlrev_b32_e32 v242, 16, v213
	v_and_b32_e32 v243, 0xffff0000, v213
	v_max_f32_e32 v242, 0x21800000, v242
	v_max_f32_e32 v243, 0x21800000, v243
	v_max_f32_e32 v228, 0x21800000, v228
	v_max_f32_e32 v229, 0x21800000, v229
	v_rcp_f32_e32 v242, v242
	v_rcp_f32_e32 v243, v243
	v_mul_f32_e32 v228, v228, v242
	v_mul_f32_e32 v229, v229, v243
	v_pk_mul_f32 v[76:77], v[76:77], v[228:229]
	v_lshlrev_b32_e32 v218, 16, v158
	v_and_b32_e32 v219, 0xffff0000, v158
	v_lshlrev_b32_e32 v220, 16, v214
	v_and_b32_e32 v221, 0xffff0000, v214
	v_max_f32_e32 v220, 0x21800000, v220
	v_max_f32_e32 v221, 0x21800000, v221
	v_max_f32_e32 v218, 0x21800000, v218
	v_max_f32_e32 v219, 0x21800000, v219
	v_rcp_f32_e32 v220, v220
	v_rcp_f32_e32 v221, v221
	v_mul_f32_e32 v218, v218, v220
	v_mul_f32_e32 v219, v219, v221
	v_pk_mul_f32 v[70:71], v[70:71], v[218:219]
	v_lshlrev_b32_e32 v228, 16, v159
	v_and_b32_e32 v229, 0xffff0000, v159
	v_lshlrev_b32_e32 v242, 16, v215
	v_and_b32_e32 v243, 0xffff0000, v215
	v_max_f32_e32 v242, 0x21800000, v242
	v_max_f32_e32 v243, 0x21800000, v243
	v_max_f32_e32 v228, 0x21800000, v228
	v_max_f32_e32 v229, 0x21800000, v229
	v_rcp_f32_e32 v242, v242
	v_rcp_f32_e32 v243, v243
	v_mul_f32_e32 v228, v228, v242
	v_mul_f32_e32 v229, v229, v243
	v_pk_mul_f32 v[72:73], v[72:73], v[228:229]
	v_lshlrev_b32_e32 v218, 16, v160
	v_and_b32_e32 v219, 0xffff0000, v160
	v_lshlrev_b32_e32 v220, 16, v216
	v_and_b32_e32 v221, 0xffff0000, v216
	v_max_f32_e32 v220, 0x21800000, v220
	v_max_f32_e32 v221, 0x21800000, v221
	v_max_f32_e32 v218, 0x21800000, v218
	v_max_f32_e32 v219, 0x21800000, v219
	v_rcp_f32_e32 v220, v220
	v_rcp_f32_e32 v221, v221
	v_mul_f32_e32 v218, v218, v220
	v_mul_f32_e32 v219, v219, v221
	v_pk_mul_f32 v[66:67], v[66:67], v[218:219]
	v_lshlrev_b32_e32 v228, 16, v161
	v_and_b32_e32 v229, 0xffff0000, v161
	v_lshlrev_b32_e32 v242, 16, v217
	v_and_b32_e32 v243, 0xffff0000, v217
	v_max_f32_e32 v242, 0x21800000, v242
	v_max_f32_e32 v243, 0x21800000, v243
	v_max_f32_e32 v228, 0x21800000, v228
	v_max_f32_e32 v229, 0x21800000, v229
	v_rcp_f32_e32 v242, v242
	v_rcp_f32_e32 v243, v243
	v_mul_f32_e32 v228, v228, v242
	v_mul_f32_e32 v229, v229, v243
	v_pk_mul_f32 v[68:69], v[68:69], v[228:229]
	v_lshl_add_u64 v[222:223], v[222:223], 0, s[44:45]
	v_lshl_add_u64 v[224:225], v[224:225], 0, s[44:45]
	global_load_dwordx4 v[130:133], v[222:223], off
	global_load_dwordx4 v[186:189], v[224:225], off
	global_load_dwordx4 v[134:137], v[222:223], off offset:256
	global_load_dwordx4 v[190:193], v[224:225], off offset:256
	v_lshl_add_u64 v[222:223], v[222:223], 0, s[8:9]
	v_lshl_add_u64 v[224:225], v[224:225], 0, s[8:9]
	global_load_dwordx4 v[138:141], v[222:223], off
	global_load_dwordx4 v[194:197], v[224:225], off
	global_load_dwordx4 v[142:145], v[222:223], off offset:256
	global_load_dwordx4 v[198:201], v[224:225], off offset:256
	v_lshl_add_u64 v[222:223], v[222:223], 0, s[8:9]
	v_lshl_add_u64 v[224:225], v[224:225], 0, s[8:9]
	global_load_dwordx4 v[146:149], v[222:223], off
	global_load_dwordx4 v[202:205], v[224:225], off
	global_load_dwordx4 v[150:153], v[222:223], off offset:256
	global_load_dwordx4 v[206:209], v[224:225], off offset:256
	v_lshl_add_u64 v[222:223], v[222:223], 0, s[8:9]
	v_lshl_add_u64 v[224:225], v[224:225], 0, s[8:9]
	global_load_dwordx4 v[154:157], v[222:223], off
	global_load_dwordx4 v[210:213], v[224:225], off
	global_load_dwordx4 v[158:161], v[222:223], off offset:256
	global_load_dwordx4 v[214:217], v[224:225], off offset:256
	s_waitcnt vmcnt(0)
; __device__ __forceinline__ float bf_lo(unsigned w) { return __uint_as_float(w << 16); }
; __device__ __forceinline__ float bf_hi(unsigned w) { return __uint_as_float(w & 0xffff0000u); }
;     __device__ __forceinline__ void operator()(const f32x4 (&acc)[2][2][4][2], const Unit& u, int wr, int wc, int fr, int fq) const {
;     ...
;                 for (int bj = 0; bj < 2; ++bj) { const int row = row0 + ai * HALF + m * 16, col = col0 + bj * HALF;
;                     gv[m][bj] = *(const u32x4*)(G + (size_t)row * NGATE + br * 2048 + col);
;                     if (br > 0) { bf16_t* mp = Mg + (size_t)row * DM + col;
;                         q0[m][bj] = __hip_atomic_load((unsigned long long*)mp, __ATOMIC_RELAXED, __HIP_MEMORY_SCOPE_AGENT);
;                         q1[m][bj] = __hip_atomic_load((unsigned long long*)mp + 1, __ATOMIC_RELAXED, __HIP_MEMORY_SCOPE_AGENT); } }
; #pragma unroll
;             for (int m = 0; m < 4; ++m)
; #pragma unroll
;                 for (int bj = 0; bj < 2; ++bj) { const int row = row0 + ai * HALF + m * 16, col = col0 + bj * HALF; const u32x4 g4 = gv[m][bj];
;                     const f32x4 a0 = acc[ai][bj][m][0], a1 = acc[ai][bj][m][1];
;                     float f0 = a0[0] * bf_lo(g4.x), f1 = a0[1] * bf_hi(g4.x), f2 = a0[2] * bf_lo(g4.y), f3 = a0[3] * bf_hi(g4.y);
;                     float f4 = a1[0] * bf_lo(g4.z), f5 = a1[1] * bf_hi(g4.z), f6 = a1[2] * bf_lo(g4.w), f7 = a1[3] * bf_hi(g4.w);
;                     if (br > 0) {
;                         const unsigned p0 = (unsigned)q0[m][bj], p1 = (unsigned)(q0[m][bj] >> 32), p2 = (unsigned)q1[m][bj], p3 = (unsigned)(q1[m][bj] >> 32);
;                         f0 += bf_lo(p0); f1 += bf_hi(p0); f2 += bf_lo(p1); f3 += bf_hi(p1); f4 += bf_lo(p2); f5 += bf_hi(p2); f6 += bf_lo(p3); f7 += bf_hi(p3);
	v_lshlrev_b32_e32 v218, 16, v130
	v_and_b32_e32 v219, 0xffff0000, v130
	v_lshlrev_b32_e32 v220, 16, v186
	v_and_b32_e32 v221, 0xffff0000, v186
	v_max_f32_e32 v220, 0x21800000, v220
	v_max_f32_e32 v221, 0x21800000, v221
	v_max_f32_e32 v218, 0x21800000, v218
	v_max_f32_e32 v219, 0x21800000, v219
	v_rcp_f32_e32 v220, v220
	v_rcp_f32_e32 v221, v221
	v_mul_f32_e32 v218, v218, v220
	v_mul_f32_e32 v219, v219, v221
	v_pk_mul_f32 v[62:63], v[62:63], v[218:219]
	v_lshlrev_b32_e32 v228, 16, v131
	v_and_b32_e32 v229, 0xffff0000, v131
	v_lshlrev_b32_e32 v242, 16, v187
	v_and_b32_e32 v243, 0xffff0000, v187
	v_max_f32_e32 v242, 0x21800000, v242
	v_max_f32_e32 v243, 0x21800000, v243
	v_max_f32_e32 v228, 0x21800000, v228
	v_max_f32_e32 v229, 0x21800000, v229
	v_rcp_f32_e32 v242, v242
	v_rcp_f32_e32 v243, v243
	v_mul_f32_e32 v228, v228, v242
	v_mul_f32_e32 v229, v229, v243
	v_pk_mul_f32 v[64:65], v[64:65], v[228:229]
	v_lshlrev_b32_e32 v218, 16, v132
	v_and_b32_e32 v219, 0xffff0000, v132
	v_lshlrev_b32_e32 v220, 16, v188
	v_and_b32_e32 v221, 0xffff0000, v188
	v_max_f32_e32 v220, 0x21800000, v220
	v_max_f32_e32 v221, 0x21800000, v221
	v_max_f32_e32 v218, 0x21800000, v218
	v_max_f32_e32 v219, 0x21800000, v219
	v_rcp_f32_e32 v220, v220
	v_rcp_f32_e32 v221, v221
	v_mul_f32_e32 v218, v218, v220
	v_mul_f32_e32 v219, v219, v221
	v_pk_mul_f32 v[58:59], v[58:59], v[218:219]
	v_lshlrev_b32_e32 v228, 16, v133
	v_and_b32_e32 v229, 0xffff0000, v133
	v_lshlrev_b32_e32 v242, 16, v189
	v_and_b32_e32 v243, 0xffff0000, v189
	v_max_f32_e32 v242, 0x21800000, v242
	v_max_f32_e32 v243, 0x21800000, v243
	v_max_f32_e32 v228, 0x21800000, v228
	v_max_f32_e32 v229, 0x21800000, v229
	v_rcp_f32_e32 v242, v242
	v_rcp_f32_e32 v243, v243
	v_mul_f32_e32 v228, v228, v242
	v_mul_f32_e32 v229, v229, v243
	v_pk_mul_f32 v[60:61], v[60:61], v[228:229]
	v_lshlrev_b32_e32 v218, 16, v134
	v_and_b32_e32 v219, 0xffff0000, v134
	v_lshlrev_b32_e32 v220, 16, v190
	v_and_b32_e32 v221, 0xffff0000, v190
	v_max_f32_e32 v220, 0x21800000, v220
	v_max_f32_e32 v221, 0x21800000, v221
	v_max_f32_e32 v218, 0x21800000, v218
	v_max_f32_e32 v219, 0x21800000, v219
	v_rcp_f32_e32 v220, v220
	v_rcp_f32_e32 v221, v221
	v_mul_f32_e32 v218, v218, v220
	v_mul_f32_e32 v219, v219, v221
	v_pk_mul_f32 v[54:55], v[54:55], v[218:219]
	v_lshlrev_b32_e32 v228, 16, v135
	v_and_b32_e32 v229, 0xffff0000, v135
	v_lshlrev_b32_e32 v242, 16, v191
	v_and_b32_e32 v243, 0xffff0000, v191
	v_max_f32_e32 v242, 0x21800000, v242
	v_max_f32_e32 v243, 0x21800000, v243
	v_max_f32_e32 v228, 0x21800000, v228
	v_max_f32_e32 v229, 0x21800000, v229
	v_rcp_f32_e32 v242, v242
	v_rcp_f32_e32 v243, v243
	v_mul_f32_e32 v228, v228, v242
	v_mul_f32_e32 v229, v229, v243
	v_pk_mul_f32 v[56:57], v[56:57], v[228:229]
	v_lshlrev_b32_e32 v218, 16, v136
	v_and_b32_e32 v219, 0xffff0000, v136
	v_lshlrev_b32_e32 v220, 16, v192
	v_and_b32_e32 v221, 0xffff0000, v192
	v_max_f32_e32 v220, 0x21800000, v220
	v_max_f32_e32 v221, 0x21800000, v221
	v_max_f32_e32 v218, 0x21800000, v218
	v_max_f32_e32 v219, 0x21800000, v219
	v_rcp_f32_e32 v220, v220
	v_rcp_f32_e32 v221, v221
	v_mul_f32_e32 v218, v218, v220
	v_mul_f32_e32 v219, v219, v221
	v_pk_mul_f32 v[50:51], v[50:51], v[218:219]
	v_lshlrev_b32_e32 v228, 16, v137
	v_and_b32_e32 v229, 0xffff0000, v137
	v_lshlrev_b32_e32 v242, 16, v193
	v_and_b32_e32 v243, 0xffff0000, v193
	v_max_f32_e32 v242, 0x21800000, v242
	v_max_f32_e32 v243, 0x21800000, v243
	v_max_f32_e32 v228, 0x21800000, v228
	v_max_f32_e32 v229, 0x21800000, v229
	v_rcp_f32_e32 v242, v242
	v_rcp_f32_e32 v243, v243
	v_mul_f32_e32 v228, v228, v242
	v_mul_f32_e32 v229, v229, v243
	v_pk_mul_f32 v[52:53], v[52:53], v[228:229]
	v_lshlrev_b32_e32 v218, 16, v138
	v_and_b32_e32 v219, 0xffff0000, v138
	v_lshlrev_b32_e32 v220, 16, v194
	v_and_b32_e32 v221, 0xffff0000, v194
	v_max_f32_e32 v220, 0x21800000, v220
	v_max_f32_e32 v221, 0x21800000, v221
	v_max_f32_e32 v218, 0x21800000, v218
	v_max_f32_e32 v219, 0x21800000, v219
	v_rcp_f32_e32 v220, v220
	v_rcp_f32_e32 v221, v221
	v_mul_f32_e32 v218, v218, v220
	v_mul_f32_e32 v219, v219, v221
	v_pk_mul_f32 v[46:47], v[46:47], v[218:219]
	v_lshlrev_b32_e32 v228, 16, v139
	v_and_b32_e32 v229, 0xffff0000, v139
	v_lshlrev_b32_e32 v242, 16, v195
	v_and_b32_e32 v243, 0xffff0000, v195
	v_max_f32_e32 v242, 0x21800000, v242
	v_max_f32_e32 v243, 0x21800000, v243
	v_max_f32_e32 v228, 0x21800000, v228
	v_max_f32_e32 v229, 0x21800000, v229
	v_rcp_f32_e32 v242, v242
	v_rcp_f32_e32 v243, v243
	v_mul_f32_e32 v228, v228, v242
	v_mul_f32_e32 v229, v229, v243
	v_pk_mul_f32 v[48:49], v[48:49], v[228:229]
	v_lshlrev_b32_e32 v218, 16, v140
	v_and_b32_e32 v219, 0xffff0000, v140
	v_lshlrev_b32_e32 v220, 16, v196
	v_and_b32_e32 v221, 0xffff0000, v196
	v_max_f32_e32 v220, 0x21800000, v220
	v_max_f32_e32 v221, 0x21800000, v221
	v_max_f32_e32 v218, 0x21800000, v218
	v_max_f32_e32 v219, 0x21800000, v219
	v_rcp_f32_e32 v220, v220
	v_rcp_f32_e32 v221, v221
	v_mul_f32_e32 v218, v218, v220
	v_mul_f32_e32 v219, v219, v221
	v_pk_mul_f32 v[42:43], v[42:43], v[218:219]
	v_lshlrev_b32_e32 v228, 16, v141
	v_and_b32_e32 v229, 0xffff0000, v141
	v_lshlrev_b32_e32 v242, 16, v197
	v_and_b32_e32 v243, 0xffff0000, v197
	v_max_f32_e32 v242, 0x21800000, v242
	v_max_f32_e32 v243, 0x21800000, v243
	v_max_f32_e32 v228, 0x21800000, v228
	v_max_f32_e32 v229, 0x21800000, v229
	v_rcp_f32_e32 v242, v242
	v_rcp_f32_e32 v243, v243
	v_mul_f32_e32 v228, v228, v242
	v_mul_f32_e32 v229, v229, v243
	v_pk_mul_f32 v[44:45], v[44:45], v[228:229]
	v_lshlrev_b32_e32 v218, 16, v142
	v_and_b32_e32 v219, 0xffff0000, v142
	v_lshlrev_b32_e32 v220, 16, v198
	v_and_b32_e32 v221, 0xffff0000, v198
; __device__ __forceinline__ float bf_lo(unsigned w) { return __uint_as_float(w << 16); }
; __device__ __forceinline__ float bf_hi(unsigned w) { return __uint_as_float(w & 0xffff0000u); }
;     __device__ __forceinline__ void operator()(const f32x4 (&acc)[2][2][4][2], const Unit& u, int wr, int wc, int fr, int fq) const {
;     ...
;                 for (int bj = 0; bj < 2; ++bj) { const int row = row0 + ai * HALF + m * 16, col = col0 + bj * HALF;
;                     gv[m][bj] = *(const u32x4*)(G + (size_t)row * NGATE + br * 2048 + col);
;                     if (br > 0) { bf16_t* mp = Mg + (size_t)row * DM + col;
;                         q0[m][bj] = __hip_atomic_load((unsigned long long*)mp, __ATOMIC_RELAXED, __HIP_MEMORY_SCOPE_AGENT);
;                         q1[m][bj] = __hip_atomic_load((unsigned long long*)mp + 1, __ATOMIC_RELAXED, __HIP_MEMORY_SCOPE_AGENT); } }
; #pragma unroll
;             for (int m = 0; m < 4; ++m)
; #pragma unroll
;                 for (int bj = 0; bj < 2; ++bj) { const int row = row0 + ai * HALF + m * 16, col = col0 + bj * HALF; const u32x4 g4 = gv[m][bj];
;                     const f32x4 a0 = acc[ai][bj][m][0], a1 = acc[ai][bj][m][1];
;                     float f0 = a0[0] * bf_lo(g4.x), f1 = a0[1] * bf_hi(g4.x), f2 = a0[2] * bf_lo(g4.y), f3 = a0[3] * bf_hi(g4.y);
;                     float f4 = a1[0] * bf_lo(g4.z), f5 = a1[1] * bf_hi(g4.z), f6 = a1[2] * bf_lo(g4.w), f7 = a1[3] * bf_hi(g4.w);
;                     if (br > 0) {
;                         const unsigned p0 = (unsigned)q0[m][bj], p1 = (unsigned)(q0[m][bj] >> 32), p2 = (unsigned)q1[m][bj], p3 = (unsigned)(q1[m][bj] >> 32);
;                         f0 += bf_lo(p0); f1 += bf_hi(p0); f2 += bf_lo(p1); f3 += bf_hi(p1); f4 += bf_lo(p2); f5 += bf_hi(p2); f6 += bf_lo(p3); f7 += bf_hi(p3);
	v_max_f32_e32 v220, 0x21800000, v220
	v_max_f32_e32 v221, 0x21800000, v221
	v_max_f32_e32 v218, 0x21800000, v218
	v_max_f32_e32 v219, 0x21800000, v219
	v_rcp_f32_e32 v220, v220
	v_rcp_f32_e32 v221, v221
	v_mul_f32_e32 v218, v218, v220
	v_mul_f32_e32 v219, v219, v221
	v_pk_mul_f32 v[38:39], v[38:39], v[218:219]
	v_lshlrev_b32_e32 v228, 16, v143
	v_and_b32_e32 v229, 0xffff0000, v143
	v_lshlrev_b32_e32 v242, 16, v199
	v_and_b32_e32 v243, 0xffff0000, v199
	v_max_f32_e32 v242, 0x21800000, v242
	v_max_f32_e32 v243, 0x21800000, v243
	v_max_f32_e32 v228, 0x21800000, v228
	v_max_f32_e32 v229, 0x21800000, v229
	v_rcp_f32_e32 v242, v242
	v_rcp_f32_e32 v243, v243
	v_mul_f32_e32 v228, v228, v242
	v_mul_f32_e32 v229, v229, v243
	v_pk_mul_f32 v[40:41], v[40:41], v[228:229]
	v_lshlrev_b32_e32 v218, 16, v144
	v_and_b32_e32 v219, 0xffff0000, v144
	v_lshlrev_b32_e32 v220, 16, v200
	v_and_b32_e32 v221, 0xffff0000, v200
	v_max_f32_e32 v220, 0x21800000, v220
	v_max_f32_e32 v221, 0x21800000, v221
	v_max_f32_e32 v218, 0x21800000, v218
	v_max_f32_e32 v219, 0x21800000, v219
	v_rcp_f32_e32 v220, v220
	v_rcp_f32_e32 v221, v221
	v_mul_f32_e32 v218, v218, v220
	v_mul_f32_e32 v219, v219, v221
	v_pk_mul_f32 v[34:35], v[34:35], v[218:219]
	v_lshlrev_b32_e32 v228, 16, v145
	v_and_b32_e32 v229, 0xffff0000, v145
	v_lshlrev_b32_e32 v242, 16, v201
	v_and_b32_e32 v243, 0xffff0000, v201
	v_max_f32_e32 v242, 0x21800000, v242
	v_max_f32_e32 v243, 0x21800000, v243
	v_max_f32_e32 v228, 0x21800000, v228
	v_max_f32_e32 v229, 0x21800000, v229
	v_rcp_f32_e32 v242, v242
	v_rcp_f32_e32 v243, v243
	v_mul_f32_e32 v228, v228, v242
	v_mul_f32_e32 v229, v229, v243
	v_pk_mul_f32 v[36:37], v[36:37], v[228:229]
	v_lshlrev_b32_e32 v218, 16, v146
	v_and_b32_e32 v219, 0xffff0000, v146
	v_lshlrev_b32_e32 v220, 16, v202
	v_and_b32_e32 v221, 0xffff0000, v202
	v_max_f32_e32 v220, 0x21800000, v220
	v_max_f32_e32 v221, 0x21800000, v221
	v_max_f32_e32 v218, 0x21800000, v218
	v_max_f32_e32 v219, 0x21800000, v219
	v_rcp_f32_e32 v220, v220
	v_rcp_f32_e32 v221, v221
	v_mul_f32_e32 v218, v218, v220
	v_mul_f32_e32 v219, v219, v221
	v_pk_mul_f32 v[30:31], v[30:31], v[218:219]
	v_lshlrev_b32_e32 v228, 16, v147
	v_and_b32_e32 v229, 0xffff0000, v147
	v_lshlrev_b32_e32 v242, 16, v203
	v_and_b32_e32 v243, 0xffff0000, v203
	v_max_f32_e32 v242, 0x21800000, v242
	v_max_f32_e32 v243, 0x21800000, v243
	v_max_f32_e32 v228, 0x21800000, v228
	v_max_f32_e32 v229, 0x21800000, v229
	v_rcp_f32_e32 v242, v242
	v_rcp_f32_e32 v243, v243
	v_mul_f32_e32 v228, v228, v242
	v_mul_f32_e32 v229, v229, v243
	v_pk_mul_f32 v[32:33], v[32:33], v[228:229]
	v_lshlrev_b32_e32 v218, 16, v148
	v_and_b32_e32 v219, 0xffff0000, v148
	v_lshlrev_b32_e32 v220, 16, v204
	v_and_b32_e32 v221, 0xffff0000, v204
	v_max_f32_e32 v220, 0x21800000, v220
	v_max_f32_e32 v221, 0x21800000, v221
	v_max_f32_e32 v218, 0x21800000, v218
	v_max_f32_e32 v219, 0x21800000, v219
	v_rcp_f32_e32 v220, v220
	v_rcp_f32_e32 v221, v221
	v_mul_f32_e32 v218, v218, v220
	v_mul_f32_e32 v219, v219, v221
	v_pk_mul_f32 v[26:27], v[26:27], v[218:219]
	v_lshlrev_b32_e32 v228, 16, v149
	v_and_b32_e32 v229, 0xffff0000, v149
	v_lshlrev_b32_e32 v242, 16, v205
	v_and_b32_e32 v243, 0xffff0000, v205
	v_max_f32_e32 v242, 0x21800000, v242
	v_max_f32_e32 v243, 0x21800000, v243
	v_max_f32_e32 v228, 0x21800000, v228
	v_max_f32_e32 v229, 0x21800000, v229
	v_rcp_f32_e32 v242, v242
	v_rcp_f32_e32 v243, v243
	v_mul_f32_e32 v228, v228, v242
	v_mul_f32_e32 v229, v229, v243
	v_pk_mul_f32 v[28:29], v[28:29], v[228:229]
	v_lshlrev_b32_e32 v218, 16, v150
	v_and_b32_e32 v219, 0xffff0000, v150
	v_lshlrev_b32_e32 v220, 16, v206
	v_and_b32_e32 v221, 0xffff0000, v206
	v_max_f32_e32 v220, 0x21800000, v220
	v_max_f32_e32 v221, 0x21800000, v221
	v_max_f32_e32 v218, 0x21800000, v218
	v_max_f32_e32 v219, 0x21800000, v219
	v_rcp_f32_e32 v220, v220
	v_rcp_f32_e32 v221, v221
	v_mul_f32_e32 v218, v218, v220
	v_mul_f32_e32 v219, v219, v221
	v_pk_mul_f32 v[22:23], v[22:23], v[218:219]
	v_lshlrev_b32_e32 v228, 16, v151
	v_and_b32_e32 v229, 0xffff0000, v151
	v_lshlrev_b32_e32 v242, 16, v207
	v_and_b32_e32 v243, 0xffff0000, v207
	v_max_f32_e32 v242, 0x21800000, v242
	v_max_f32_e32 v243, 0x21800000, v243
	v_max_f32_e32 v228, 0x21800000, v228
	v_max_f32_e32 v229, 0x21800000, v229
	v_rcp_f32_e32 v242, v242
	v_rcp_f32_e32 v243, v243
	v_mul_f32_e32 v228, v228, v242
	v_mul_f32_e32 v229, v229, v243
	v_pk_mul_f32 v[24:25], v[24:25], v[228:229]
	v_lshlrev_b32_e32 v218, 16, v152
	v_and_b32_e32 v219, 0xffff0000, v152
	v_lshlrev_b32_e32 v220, 16, v208
	v_and_b32_e32 v221, 0xffff0000, v208
	v_max_f32_e32 v220, 0x21800000, v220
	v_max_f32_e32 v221, 0x21800000, v221
	v_max_f32_e32 v218, 0x21800000, v218
	v_max_f32_e32 v219, 0x21800000, v219
	v_rcp_f32_e32 v220, v220
	v_rcp_f32_e32 v221, v221
	v_mul_f32_e32 v218, v218, v220
	v_mul_f32_e32 v219, v219, v221
	v_pk_mul_f32 v[18:19], v[18:19], v[218:219]
	v_lshlrev_b32_e32 v228, 16, v153
	v_and_b32_e32 v229, 0xffff0000, v153
	v_lshlrev_b32_e32 v242, 16, v209
	v_and_b32_e32 v243, 0xffff0000, v209
	v_max_f32_e32 v242, 0x21800000, v242
	v_max_f32_e32 v243, 0x21800000, v243
	v_max_f32_e32 v228, 0x21800000, v228
	v_max_f32_e32 v229, 0x21800000, v229
	v_rcp_f32_e32 v242, v242
	v_rcp_f32_e32 v243, v243
	v_mul_f32_e32 v228, v228, v242
	v_mul_f32_e32 v229, v229, v243
	v_pk_mul_f32 v[20:21], v[20:21], v[228:229]
	v_lshlrev_b32_e32 v218, 16, v154
	v_and_b32_e32 v219, 0xffff0000, v154
	v_lshlrev_b32_e32 v220, 16, v210
	v_and_b32_e32 v221, 0xffff0000, v210
	v_max_f32_e32 v220, 0x21800000, v220
	v_max_f32_e32 v221, 0x21800000, v221
	v_max_f32_e32 v218, 0x21800000, v218
	v_max_f32_e32 v219, 0x21800000, v219
; __device__ __forceinline__ unsigned cvt_pk_bf16(float lo, float hi) { unsigned r; asm volatile("v_cvt_pk_bf16_f32 %0, %1, %2" : "=v"(r) : "v"(lo), "v"(hi)); return r; }
; __device__ __forceinline__ float bf_lo(unsigned w) { return __uint_as_float(w << 16); }
; __device__ __forceinline__ float bf_hi(unsigned w) { return __uint_as_float(w & 0xffff0000u); }
;     __device__ __forceinline__ void operator()(const f32x4 (&acc)[2][2][4][2], const Unit& u, int wr, int wc, int fr, int fq) const {
;     ...
;                 for (int bj = 0; bj < 2; ++bj) { const int row = row0 + ai * HALF + m * 16, col = col0 + bj * HALF;
;                     gv[m][bj] = *(const u32x4*)(G + (size_t)row * NGATE + br * 2048 + col);
;                     if (br > 0) { bf16_t* mp = Mg + (size_t)row * DM + col;
;                         q0[m][bj] = __hip_atomic_load((unsigned long long*)mp, __ATOMIC_RELAXED, __HIP_MEMORY_SCOPE_AGENT);
;                         q1[m][bj] = __hip_atomic_load((unsigned long long*)mp + 1, __ATOMIC_RELAXED, __HIP_MEMORY_SCOPE_AGENT); } }
; #pragma unroll
;             for (int m = 0; m < 4; ++m)
; #pragma unroll
;                 for (int bj = 0; bj < 2; ++bj) { const int row = row0 + ai * HALF + m * 16, col = col0 + bj * HALF; const u32x4 g4 = gv[m][bj];
;                     const f32x4 a0 = acc[ai][bj][m][0], a1 = acc[ai][bj][m][1];
;                     float f0 = a0[0] * bf_lo(g4.x), f1 = a0[1] * bf_hi(g4.x), f2 = a0[2] * bf_lo(g4.y), f3 = a0[3] * bf_hi(g4.y);
;                     float f4 = a1[0] * bf_lo(g4.z), f5 = a1[1] * bf_hi(g4.z), f6 = a1[2] * bf_lo(g4.w), f7 = a1[3] * bf_hi(g4.w);
;                     if (br > 0) {
;                         const unsigned p0 = (unsigned)q0[m][bj], p1 = (unsigned)(q0[m][bj] >> 32), p2 = (unsigned)q1[m][bj], p3 = (unsigned)(q1[m][bj] >> 32);
;                         f0 += bf_lo(p0); f1 += bf_hi(p0); f2 += bf_lo(p1); f3 += bf_hi(p1); f4 += bf_lo(p2); f5 += bf_hi(p2); f6 += bf_lo(p3); f7 += bf_hi(p3);
;                     }
;                     u32x4 w; w.x = cvt_pk_bf16(f0, f1); w.y = cvt_pk_bf16(f2, f3); w.z = cvt_pk_bf16(f4, f5); w.w = cvt_pk_bf16(f6, f7);
;                     *(u32x4*)(Mg + (size_t)row * DM + col) = w; }
	v_rcp_f32_e32 v220, v220
	v_rcp_f32_e32 v221, v221
	v_mul_f32_e32 v218, v218, v220
	v_mul_f32_e32 v219, v219, v221
	v_pk_mul_f32 v[14:15], v[14:15], v[218:219]
	v_lshlrev_b32_e32 v228, 16, v155
	v_and_b32_e32 v229, 0xffff0000, v155
	v_lshlrev_b32_e32 v242, 16, v211
	v_and_b32_e32 v243, 0xffff0000, v211
	v_max_f32_e32 v242, 0x21800000, v242
	v_max_f32_e32 v243, 0x21800000, v243
	v_max_f32_e32 v228, 0x21800000, v228
	v_max_f32_e32 v229, 0x21800000, v229
	v_rcp_f32_e32 v242, v242
	v_rcp_f32_e32 v243, v243
	v_mul_f32_e32 v228, v228, v242
	v_mul_f32_e32 v229, v229, v243
	v_pk_mul_f32 v[16:17], v[16:17], v[228:229]
	v_lshlrev_b32_e32 v218, 16, v156
	v_and_b32_e32 v219, 0xffff0000, v156
	v_lshlrev_b32_e32 v220, 16, v212
	v_and_b32_e32 v221, 0xffff0000, v212
	v_max_f32_e32 v220, 0x21800000, v220
	v_max_f32_e32 v221, 0x21800000, v221
	v_max_f32_e32 v218, 0x21800000, v218
	v_max_f32_e32 v219, 0x21800000, v219
	v_rcp_f32_e32 v220, v220
	v_rcp_f32_e32 v221, v221
	v_mul_f32_e32 v218, v218, v220
	v_mul_f32_e32 v219, v219, v221
	v_pk_mul_f32 v[10:11], v[10:11], v[218:219]
	v_lshlrev_b32_e32 v228, 16, v157
	v_and_b32_e32 v229, 0xffff0000, v157
	v_lshlrev_b32_e32 v242, 16, v213
	v_and_b32_e32 v243, 0xffff0000, v213
	v_max_f32_e32 v242, 0x21800000, v242
	v_max_f32_e32 v243, 0x21800000, v243
	v_max_f32_e32 v228, 0x21800000, v228
	v_max_f32_e32 v229, 0x21800000, v229
	v_rcp_f32_e32 v242, v242
	v_rcp_f32_e32 v243, v243
	v_mul_f32_e32 v228, v228, v242
	v_mul_f32_e32 v229, v229, v243
	v_pk_mul_f32 v[12:13], v[12:13], v[228:229]
	v_lshlrev_b32_e32 v218, 16, v158
	v_and_b32_e32 v219, 0xffff0000, v158
	v_lshlrev_b32_e32 v220, 16, v214
	v_and_b32_e32 v221, 0xffff0000, v214
	v_max_f32_e32 v220, 0x21800000, v220
	v_max_f32_e32 v221, 0x21800000, v221
	v_max_f32_e32 v218, 0x21800000, v218
	v_max_f32_e32 v219, 0x21800000, v219
	v_rcp_f32_e32 v220, v220
	v_rcp_f32_e32 v221, v221
	v_mul_f32_e32 v218, v218, v220
	v_mul_f32_e32 v219, v219, v221
	v_pk_mul_f32 v[6:7], v[6:7], v[218:219]
	v_lshlrev_b32_e32 v228, 16, v159
	v_and_b32_e32 v229, 0xffff0000, v159
	v_lshlrev_b32_e32 v242, 16, v215
	v_and_b32_e32 v243, 0xffff0000, v215
	v_max_f32_e32 v242, 0x21800000, v242
	v_max_f32_e32 v243, 0x21800000, v243
	v_max_f32_e32 v228, 0x21800000, v228
	v_max_f32_e32 v229, 0x21800000, v229
	v_rcp_f32_e32 v242, v242
	v_rcp_f32_e32 v243, v243
	v_mul_f32_e32 v228, v228, v242
	v_mul_f32_e32 v229, v229, v243
	v_pk_mul_f32 v[8:9], v[8:9], v[228:229]
	v_lshlrev_b32_e32 v218, 16, v160
	v_and_b32_e32 v219, 0xffff0000, v160
	v_lshlrev_b32_e32 v220, 16, v216
	v_and_b32_e32 v221, 0xffff0000, v216
	v_max_f32_e32 v220, 0x21800000, v220
	v_max_f32_e32 v221, 0x21800000, v221
	v_max_f32_e32 v218, 0x21800000, v218
	v_max_f32_e32 v219, 0x21800000, v219
	v_rcp_f32_e32 v220, v220
	v_rcp_f32_e32 v221, v221
	v_mul_f32_e32 v218, v218, v220
	v_mul_f32_e32 v219, v219, v221
	v_pk_mul_f32 v[2:3], v[2:3], v[218:219]
	v_lshlrev_b32_e32 v228, 16, v161
	v_and_b32_e32 v229, 0xffff0000, v161
	v_lshlrev_b32_e32 v242, 16, v217
	v_and_b32_e32 v243, 0xffff0000, v217
	v_max_f32_e32 v242, 0x21800000, v242
	v_max_f32_e32 v243, 0x21800000, v243
	v_max_f32_e32 v228, 0x21800000, v228
	v_max_f32_e32 v229, 0x21800000, v229
	v_rcp_f32_e32 v242, v242
	v_rcp_f32_e32 v243, v243
	v_mul_f32_e32 v228, v228, v242
	v_mul_f32_e32 v229, v229, v243
	v_pk_mul_f32 v[4:5], v[4:5], v[228:229]
	s_branch .Lrb_tail
.Lrb_final:
	global_load_dwordx4 v[130:133], v[222:223], off
	global_load_dwordx4 v[134:137], v[222:223], off offset:256
	v_lshl_add_u64 v[222:223], v[222:223], 0, s[8:9]
	global_load_dwordx4 v[138:141], v[222:223], off
	global_load_dwordx4 v[142:145], v[222:223], off offset:256
	v_lshl_add_u64 v[222:223], v[222:223], 0, s[8:9]
	global_load_dwordx4 v[146:149], v[222:223], off
	global_load_dwordx4 v[150:153], v[222:223], off offset:256
	v_lshl_add_u64 v[222:223], v[222:223], 0, s[8:9]
	global_load_dwordx4 v[154:157], v[222:223], off
	global_load_dwordx4 v[158:161], v[222:223], off offset:256
	s_waitcnt vmcnt(0)
	v_lshlrev_b32_e32 v218, 16, v130
	v_and_b32_e32 v219, 0xffff0000, v130
	v_max_f32_e32 v218, 0x21800000, v218
	v_max_f32_e32 v219, 0x21800000, v219
	v_pk_mul_f32 v[126:127], v[126:127], v[218:219]
	v_lshlrev_b32_e32 v228, 16, v131
	v_and_b32_e32 v229, 0xffff0000, v131
	v_max_f32_e32 v228, 0x21800000, v228
	v_max_f32_e32 v229, 0x21800000, v229
	v_pk_mul_f32 v[128:129], v[128:129], v[228:229]
	v_lshlrev_b32_e32 v218, 16, v132
	v_and_b32_e32 v219, 0xffff0000, v132
	v_max_f32_e32 v218, 0x21800000, v218
	v_max_f32_e32 v219, 0x21800000, v219
	v_pk_mul_f32 v[122:123], v[122:123], v[218:219]
	v_lshlrev_b32_e32 v228, 16, v133
	v_and_b32_e32 v229, 0xffff0000, v133
	v_max_f32_e32 v228, 0x21800000, v228
	v_max_f32_e32 v229, 0x21800000, v229
	v_pk_mul_f32 v[124:125], v[124:125], v[228:229]
	v_cvt_pk_bf16_f32 v126, v126, v127
	v_cvt_pk_bf16_f32 v127, v128, v129
	v_cvt_pk_bf16_f32 v128, v122, v123
	v_cvt_pk_bf16_f32 v129, v124, v125
	global_store_dwordx4 v[226:227], v[126:129], off
	v_lshlrev_b32_e32 v218, 16, v134
	v_and_b32_e32 v219, 0xffff0000, v134
	v_max_f32_e32 v218, 0x21800000, v218
	v_max_f32_e32 v219, 0x21800000, v219
	v_pk_mul_f32 v[118:119], v[118:119], v[218:219]
	v_lshlrev_b32_e32 v228, 16, v135
	v_and_b32_e32 v229, 0xffff0000, v135
	v_max_f32_e32 v228, 0x21800000, v228
	v_max_f32_e32 v229, 0x21800000, v229
	v_pk_mul_f32 v[120:121], v[120:121], v[228:229]
	v_lshlrev_b32_e32 v218, 16, v136
	v_and_b32_e32 v219, 0xffff0000, v136
	v_max_f32_e32 v218, 0x21800000, v218
	v_max_f32_e32 v219, 0x21800000, v219
	v_pk_mul_f32 v[114:115], v[114:115], v[218:219]
	v_lshlrev_b32_e32 v228, 16, v137
	v_and_b32_e32 v229, 0xffff0000, v137
; __device__ __forceinline__ unsigned cvt_pk_bf16(float lo, float hi) { unsigned r; asm volatile("v_cvt_pk_bf16_f32 %0, %1, %2" : "=v"(r) : "v"(lo), "v"(hi)); return r; }
; __device__ __forceinline__ float bf_lo(unsigned w) { return __uint_as_float(w << 16); }
; __device__ __forceinline__ float bf_hi(unsigned w) { return __uint_as_float(w & 0xffff0000u); }
;     __device__ __forceinline__ void operator()(const f32x4 (&acc)[2][2][4][2], const Unit& u, int wr, int wc, int fr, int fq) const {
;     ...
;             for (int m = 0; m < 4; ++m)
; #pragma unroll
;                 for (int bj = 0; bj < 2; ++bj) { const int row = row0 + ai * HALF + m * 16, col = col0 + bj * HALF; const u32x4 g4 = gv[m][bj];
;                     const f32x4 a0 = acc[ai][bj][m][0], a1 = acc[ai][bj][m][1];
;                     float f0 = a0[0] * bf_lo(g4.x), f1 = a0[1] * bf_hi(g4.x), f2 = a0[2] * bf_lo(g4.y), f3 = a0[3] * bf_hi(g4.y);
;                     float f4 = a1[0] * bf_lo(g4.z), f5 = a1[1] * bf_hi(g4.z), f6 = a1[2] * bf_lo(g4.w), f7 = a1[3] * bf_hi(g4.w);
;                     if (br > 0) {
;                         const unsigned p0 = (unsigned)q0[m][bj], p1 = (unsigned)(q0[m][bj] >> 32), p2 = (unsigned)q1[m][bj], p3 = (unsigned)(q1[m][bj] >> 32);
;                         f0 += bf_lo(p0); f1 += bf_hi(p0); f2 += bf_lo(p1); f3 += bf_hi(p1); f4 += bf_lo(p2); f5 += bf_hi(p2); f6 += bf_lo(p3); f7 += bf_hi(p3);
;                     }
;                     u32x4 w; w.x = cvt_pk_bf16(f0, f1); w.y = cvt_pk_bf16(f2, f3); w.z = cvt_pk_bf16(f4, f5); w.w = cvt_pk_bf16(f6, f7);
;                     *(u32x4*)(Mg + (size_t)row * DM + col) = w; }
;             asm volatile("" ::: "memory"); }
	v_max_f32_e32 v228, 0x21800000, v228
	v_max_f32_e32 v229, 0x21800000, v229
	v_pk_mul_f32 v[116:117], v[116:117], v[228:229]
	v_cvt_pk_bf16_f32 v118, v118, v119
	v_cvt_pk_bf16_f32 v119, v120, v121
	v_cvt_pk_bf16_f32 v120, v114, v115
	v_cvt_pk_bf16_f32 v121, v116, v117
	global_store_dwordx4 v[226:227], v[118:121], off offset:256
	v_lshlrev_b32_e32 v218, 16, v138
	v_and_b32_e32 v219, 0xffff0000, v138
	v_max_f32_e32 v218, 0x21800000, v218
	v_max_f32_e32 v219, 0x21800000, v219
	v_pk_mul_f32 v[110:111], v[110:111], v[218:219]
	v_lshlrev_b32_e32 v228, 16, v139
	v_and_b32_e32 v229, 0xffff0000, v139
	v_max_f32_e32 v228, 0x21800000, v228
	v_max_f32_e32 v229, 0x21800000, v229
	v_pk_mul_f32 v[112:113], v[112:113], v[228:229]
	v_lshlrev_b32_e32 v218, 16, v140
	v_and_b32_e32 v219, 0xffff0000, v140
	v_max_f32_e32 v218, 0x21800000, v218
	v_max_f32_e32 v219, 0x21800000, v219
	v_pk_mul_f32 v[106:107], v[106:107], v[218:219]
	v_lshlrev_b32_e32 v228, 16, v141
	v_and_b32_e32 v229, 0xffff0000, v141
	v_max_f32_e32 v228, 0x21800000, v228
	v_max_f32_e32 v229, 0x21800000, v229
	v_pk_mul_f32 v[108:109], v[108:109], v[228:229]
	v_cvt_pk_bf16_f32 v110, v110, v111
	v_cvt_pk_bf16_f32 v111, v112, v113
	v_cvt_pk_bf16_f32 v112, v106, v107
	v_cvt_pk_bf16_f32 v113, v108, v109
	v_lshl_add_u64 v[226:227], v[226:227], 0, s[46:47]
	global_store_dwordx4 v[226:227], v[110:113], off
	v_lshlrev_b32_e32 v218, 16, v142
	v_and_b32_e32 v219, 0xffff0000, v142
	v_max_f32_e32 v218, 0x21800000, v218
	v_max_f32_e32 v219, 0x21800000, v219
	v_pk_mul_f32 v[102:103], v[102:103], v[218:219]
	v_lshlrev_b32_e32 v228, 16, v143
	v_and_b32_e32 v229, 0xffff0000, v143
	v_max_f32_e32 v228, 0x21800000, v228
	v_max_f32_e32 v229, 0x21800000, v229
	v_pk_mul_f32 v[104:105], v[104:105], v[228:229]
	v_lshlrev_b32_e32 v218, 16, v144
	v_and_b32_e32 v219, 0xffff0000, v144
	v_max_f32_e32 v218, 0x21800000, v218
	v_max_f32_e32 v219, 0x21800000, v219
	v_pk_mul_f32 v[98:99], v[98:99], v[218:219]
	v_lshlrev_b32_e32 v228, 16, v145
	v_and_b32_e32 v229, 0xffff0000, v145
	v_max_f32_e32 v228, 0x21800000, v228
	v_max_f32_e32 v229, 0x21800000, v229
	v_pk_mul_f32 v[100:101], v[100:101], v[228:229]
	v_cvt_pk_bf16_f32 v102, v102, v103
	v_cvt_pk_bf16_f32 v103, v104, v105
	v_cvt_pk_bf16_f32 v104, v98, v99
	v_cvt_pk_bf16_f32 v105, v100, v101
	global_store_dwordx4 v[226:227], v[102:105], off offset:256
	v_lshlrev_b32_e32 v218, 16, v146
	v_and_b32_e32 v219, 0xffff0000, v146
	v_max_f32_e32 v218, 0x21800000, v218
	v_max_f32_e32 v219, 0x21800000, v219
	v_pk_mul_f32 v[94:95], v[94:95], v[218:219]
	v_lshlrev_b32_e32 v228, 16, v147
	v_and_b32_e32 v229, 0xffff0000, v147
	v_max_f32_e32 v228, 0x21800000, v228
	v_max_f32_e32 v229, 0x21800000, v229
	v_pk_mul_f32 v[96:97], v[96:97], v[228:229]
	v_lshlrev_b32_e32 v218, 16, v148
	v_and_b32_e32 v219, 0xffff0000, v148
	v_max_f32_e32 v218, 0x21800000, v218
	v_max_f32_e32 v219, 0x21800000, v219
	v_pk_mul_f32 v[90:91], v[90:91], v[218:219]
	v_lshlrev_b32_e32 v228, 16, v149
	v_and_b32_e32 v229, 0xffff0000, v149
	v_max_f32_e32 v228, 0x21800000, v228
	v_max_f32_e32 v229, 0x21800000, v229
	v_pk_mul_f32 v[92:93], v[92:93], v[228:229]
	v_cvt_pk_bf16_f32 v94, v94, v95
	v_cvt_pk_bf16_f32 v95, v96, v97
	v_cvt_pk_bf16_f32 v96, v90, v91
	v_cvt_pk_bf16_f32 v97, v92, v93
	v_lshl_add_u64 v[226:227], v[226:227], 0, s[46:47]
	global_store_dwordx4 v[226:227], v[94:97], off
	v_lshlrev_b32_e32 v218, 16, v150
	v_and_b32_e32 v219, 0xffff0000, v150
	v_max_f32_e32 v218, 0x21800000, v218
	v_max_f32_e32 v219, 0x21800000, v219
	v_pk_mul_f32 v[86:87], v[86:87], v[218:219]
	v_lshlrev_b32_e32 v228, 16, v151
	v_and_b32_e32 v229, 0xffff0000, v151
	v_max_f32_e32 v228, 0x21800000, v228
	v_max_f32_e32 v229, 0x21800000, v229
	v_pk_mul_f32 v[88:89], v[88:89], v[228:229]
	v_lshlrev_b32_e32 v218, 16, v152
	v_and_b32_e32 v219, 0xffff0000, v152
	v_max_f32_e32 v218, 0x21800000, v218
	v_max_f32_e32 v219, 0x21800000, v219
	v_pk_mul_f32 v[82:83], v[82:83], v[218:219]
	v_lshlrev_b32_e32 v228, 16, v153
	v_and_b32_e32 v229, 0xffff0000, v153
	v_max_f32_e32 v228, 0x21800000, v228
	v_max_f32_e32 v229, 0x21800000, v229
	v_pk_mul_f32 v[84:85], v[84:85], v[228:229]
	v_cvt_pk_bf16_f32 v86, v86, v87
	v_cvt_pk_bf16_f32 v87, v88, v89
	v_cvt_pk_bf16_f32 v88, v82, v83
	v_cvt_pk_bf16_f32 v89, v84, v85
	global_store_dwordx4 v[226:227], v[86:89], off offset:256
	v_lshlrev_b32_e32 v218, 16, v154
	v_and_b32_e32 v219, 0xffff0000, v154
	v_max_f32_e32 v218, 0x21800000, v218
	v_max_f32_e32 v219, 0x21800000, v219
	v_pk_mul_f32 v[78:79], v[78:79], v[218:219]
	v_lshlrev_b32_e32 v228, 16, v155
	v_and_b32_e32 v229, 0xffff0000, v155
	v_max_f32_e32 v228, 0x21800000, v228
	v_max_f32_e32 v229, 0x21800000, v229
	v_pk_mul_f32 v[80:81], v[80:81], v[228:229]
	v_lshlrev_b32_e32 v218, 16, v156
	v_and_b32_e32 v219, 0xffff0000, v156
	v_max_f32_e32 v218, 0x21800000, v218
	v_max_f32_e32 v219, 0x21800000, v219
	v_pk_mul_f32 v[74:75], v[74:75], v[218:219]
	v_lshlrev_b32_e32 v228, 16, v157
	v_and_b32_e32 v229, 0xffff0000, v157
	v_max_f32_e32 v228, 0x21800000, v228
	v_max_f32_e32 v229, 0x21800000, v229
	v_pk_mul_f32 v[76:77], v[76:77], v[228:229]
	v_cvt_pk_bf16_f32 v78, v78, v79
	v_cvt_pk_bf16_f32 v79, v80, v81
	v_cvt_pk_bf16_f32 v80, v74, v75
	v_cvt_pk_bf16_f32 v81, v76, v77
	v_lshl_add_u64 v[226:227], v[226:227], 0, s[46:47]
	global_store_dwordx4 v[226:227], v[78:81], off
	v_lshlrev_b32_e32 v218, 16, v158
	v_and_b32_e32 v219, 0xffff0000, v158
	v_max_f32_e32 v218, 0x21800000, v218
	v_max_f32_e32 v219, 0x21800000, v219
	v_pk_mul_f32 v[70:71], v[70:71], v[218:219]
	v_lshlrev_b32_e32 v228, 16, v159
	v_and_b32_e32 v229, 0xffff0000, v159
	v_max_f32_e32 v228, 0x21800000, v228
	v_max_f32_e32 v229, 0x21800000, v229
	v_pk_mul_f32 v[72:73], v[72:73], v[228:229]
	v_lshlrev_b32_e32 v218, 16, v160
	v_and_b32_e32 v219, 0xffff0000, v160
	v_max_f32_e32 v218, 0x21800000, v218
	v_max_f32_e32 v219, 0x21800000, v219
	v_pk_mul_f32 v[66:67], v[66:67], v[218:219]
	v_lshlrev_b32_e32 v228, 16, v161
	v_and_b32_e32 v229, 0xffff0000, v161
	v_max_f32_e32 v228, 0x21800000, v228
	v_max_f32_e32 v229, 0x21800000, v229
	v_pk_mul_f32 v[68:69], v[68:69], v[228:229]
	v_cvt_pk_bf16_f32 v70, v70, v71
	v_cvt_pk_bf16_f32 v71, v72, v73
	v_cvt_pk_bf16_f32 v72, v66, v67
	v_cvt_pk_bf16_f32 v73, v68, v69
	global_store_dwordx4 v[226:227], v[70:73], off offset:256
	v_lshl_add_u64 v[222:223], v[222:223], 0, s[44:45]
	v_lshl_add_u64 v[226:227], v[226:227], 0, s[42:43]
	global_load_dwordx4 v[130:133], v[222:223], off
	global_load_dwordx4 v[134:137], v[222:223], off offset:256
	v_lshl_add_u64 v[222:223], v[222:223], 0, s[8:9]
	global_load_dwordx4 v[138:141], v[222:223], off
	global_load_dwordx4 v[142:145], v[222:223], off offset:256
	v_lshl_add_u64 v[222:223], v[222:223], 0, s[8:9]
	global_load_dwordx4 v[146:149], v[222:223], off
	global_load_dwordx4 v[150:153], v[222:223], off offset:256
	v_lshl_add_u64 v[222:223], v[222:223], 0, s[8:9]
	global_load_dwordx4 v[154:157], v[222:223], off
	global_load_dwordx4 v[158:161], v[222:223], off offset:256
	s_waitcnt vmcnt(0)
; __device__ __forceinline__ unsigned cvt_pk_bf16(float lo, float hi) { unsigned r; asm volatile("v_cvt_pk_bf16_f32 %0, %1, %2" : "=v"(r) : "v"(lo), "v"(hi)); return r; }
; __device__ __forceinline__ float bf_lo(unsigned w) { return __uint_as_float(w << 16); }
; __device__ __forceinline__ float bf_hi(unsigned w) { return __uint_as_float(w & 0xffff0000u); }
;     __device__ __forceinline__ void operator()(const f32x4 (&acc)[2][2][4][2], const Unit& u, int wr, int wc, int fr, int fq) const {
;     ...
;             for (int m = 0; m < 4; ++m)
; #pragma unroll
;                 for (int bj = 0; bj < 2; ++bj) { const int row = row0 + ai * HALF + m * 16, col = col0 + bj * HALF; const u32x4 g4 = gv[m][bj];
;                     const f32x4 a0 = acc[ai][bj][m][0], a1 = acc[ai][bj][m][1];
;                     float f0 = a0[0] * bf_lo(g4.x), f1 = a0[1] * bf_hi(g4.x), f2 = a0[2] * bf_lo(g4.y), f3 = a0[3] * bf_hi(g4.y);
;                     float f4 = a1[0] * bf_lo(g4.z), f5 = a1[1] * bf_hi(g4.z), f6 = a1[2] * bf_lo(g4.w), f7 = a1[3] * bf_hi(g4.w);
;                     if (br > 0) {
;                         const unsigned p0 = (unsigned)q0[m][bj], p1 = (unsigned)(q0[m][bj] >> 32), p2 = (unsigned)q1[m][bj], p3 = (unsigned)(q1[m][bj] >> 32);
;                         f0 += bf_lo(p0); f1 += bf_hi(p0); f2 += bf_lo(p1); f3 += bf_hi(p1); f4 += bf_lo(p2); f5 += bf_hi(p2); f6 += bf_lo(p3); f7 += bf_hi(p3);
;                     }
;                     u32x4 w; w.x = cvt_pk_bf16(f0, f1); w.y = cvt_pk_bf16(f2, f3); w.z = cvt_pk_bf16(f4, f5); w.w = cvt_pk_bf16(f6, f7);
;                     *(u32x4*)(Mg + (size_t)row * DM + col) = w; }
;             asm volatile("" ::: "memory"); }
	v_lshlrev_b32_e32 v218, 16, v130
	v_and_b32_e32 v219, 0xffff0000, v130
	v_max_f32_e32 v218, 0x21800000, v218
	v_max_f32_e32 v219, 0x21800000, v219
	v_pk_mul_f32 v[62:63], v[62:63], v[218:219]
	v_lshlrev_b32_e32 v228, 16, v131
	v_and_b32_e32 v229, 0xffff0000, v131
	v_max_f32_e32 v228, 0x21800000, v228
	v_max_f32_e32 v229, 0x21800000, v229
	v_pk_mul_f32 v[64:65], v[64:65], v[228:229]
	v_lshlrev_b32_e32 v218, 16, v132
	v_and_b32_e32 v219, 0xffff0000, v132
	v_max_f32_e32 v218, 0x21800000, v218
	v_max_f32_e32 v219, 0x21800000, v219
	v_pk_mul_f32 v[58:59], v[58:59], v[218:219]
	v_lshlrev_b32_e32 v228, 16, v133
	v_and_b32_e32 v229, 0xffff0000, v133
	v_max_f32_e32 v228, 0x21800000, v228
	v_max_f32_e32 v229, 0x21800000, v229
	v_pk_mul_f32 v[60:61], v[60:61], v[228:229]
	v_cvt_pk_bf16_f32 v62, v62, v63
	v_cvt_pk_bf16_f32 v63, v64, v65
	v_cvt_pk_bf16_f32 v64, v58, v59
	v_cvt_pk_bf16_f32 v65, v60, v61
	global_store_dwordx4 v[226:227], v[62:65], off
	v_lshlrev_b32_e32 v218, 16, v134
	v_and_b32_e32 v219, 0xffff0000, v134
	v_max_f32_e32 v218, 0x21800000, v218
	v_max_f32_e32 v219, 0x21800000, v219
	v_pk_mul_f32 v[54:55], v[54:55], v[218:219]
	v_lshlrev_b32_e32 v228, 16, v135
	v_and_b32_e32 v229, 0xffff0000, v135
	v_max_f32_e32 v228, 0x21800000, v228
	v_max_f32_e32 v229, 0x21800000, v229
	v_pk_mul_f32 v[56:57], v[56:57], v[228:229]
	v_lshlrev_b32_e32 v218, 16, v136
	v_and_b32_e32 v219, 0xffff0000, v136
	v_max_f32_e32 v218, 0x21800000, v218
	v_max_f32_e32 v219, 0x21800000, v219
	v_pk_mul_f32 v[50:51], v[50:51], v[218:219]
	v_lshlrev_b32_e32 v228, 16, v137
	v_and_b32_e32 v229, 0xffff0000, v137
	v_max_f32_e32 v228, 0x21800000, v228
	v_max_f32_e32 v229, 0x21800000, v229
	v_pk_mul_f32 v[52:53], v[52:53], v[228:229]
	v_cvt_pk_bf16_f32 v54, v54, v55
	v_cvt_pk_bf16_f32 v55, v56, v57
	v_cvt_pk_bf16_f32 v56, v50, v51
	v_cvt_pk_bf16_f32 v57, v52, v53
	global_store_dwordx4 v[226:227], v[54:57], off offset:256
	v_lshlrev_b32_e32 v218, 16, v138
	v_and_b32_e32 v219, 0xffff0000, v138
	v_max_f32_e32 v218, 0x21800000, v218
	v_max_f32_e32 v219, 0x21800000, v219
	v_pk_mul_f32 v[46:47], v[46:47], v[218:219]
	v_lshlrev_b32_e32 v228, 16, v139
	v_and_b32_e32 v229, 0xffff0000, v139
	v_max_f32_e32 v228, 0x21800000, v228
	v_max_f32_e32 v229, 0x21800000, v229
	v_pk_mul_f32 v[48:49], v[48:49], v[228:229]
	v_lshlrev_b32_e32 v218, 16, v140
	v_and_b32_e32 v219, 0xffff0000, v140
	v_max_f32_e32 v218, 0x21800000, v218
	v_max_f32_e32 v219, 0x21800000, v219
	v_pk_mul_f32 v[42:43], v[42:43], v[218:219]
	v_lshlrev_b32_e32 v228, 16, v141
	v_and_b32_e32 v229, 0xffff0000, v141
	v_max_f32_e32 v228, 0x21800000, v228
	v_max_f32_e32 v229, 0x21800000, v229
	v_pk_mul_f32 v[44:45], v[44:45], v[228:229]
	v_cvt_pk_bf16_f32 v46, v46, v47
	v_cvt_pk_bf16_f32 v47, v48, v49
	v_cvt_pk_bf16_f32 v48, v42, v43
	v_cvt_pk_bf16_f32 v49, v44, v45
	v_lshl_add_u64 v[226:227], v[226:227], 0, s[46:47]
	global_store_dwordx4 v[226:227], v[46:49], off
	v_lshlrev_b32_e32 v218, 16, v142
	v_and_b32_e32 v219, 0xffff0000, v142
	v_max_f32_e32 v218, 0x21800000, v218
	v_max_f32_e32 v219, 0x21800000, v219
	v_pk_mul_f32 v[38:39], v[38:39], v[218:219]
	v_lshlrev_b32_e32 v228, 16, v143
	v_and_b32_e32 v229, 0xffff0000, v143
	v_max_f32_e32 v228, 0x21800000, v228
	v_max_f32_e32 v229, 0x21800000, v229
	v_pk_mul_f32 v[40:41], v[40:41], v[228:229]
	v_lshlrev_b32_e32 v218, 16, v144
	v_and_b32_e32 v219, 0xffff0000, v144
	v_max_f32_e32 v218, 0x21800000, v218
	v_max_f32_e32 v219, 0x21800000, v219
	v_pk_mul_f32 v[34:35], v[34:35], v[218:219]
	v_lshlrev_b32_e32 v228, 16, v145
	v_and_b32_e32 v229, 0xffff0000, v145
	v_max_f32_e32 v228, 0x21800000, v228
	v_max_f32_e32 v229, 0x21800000, v229
	v_pk_mul_f32 v[36:37], v[36:37], v[228:229]
	v_cvt_pk_bf16_f32 v38, v38, v39
	v_cvt_pk_bf16_f32 v39, v40, v41
	v_cvt_pk_bf16_f32 v40, v34, v35
	v_cvt_pk_bf16_f32 v41, v36, v37
	global_store_dwordx4 v[226:227], v[38:41], off offset:256
	v_lshlrev_b32_e32 v218, 16, v146
	v_and_b32_e32 v219, 0xffff0000, v146
	v_max_f32_e32 v218, 0x21800000, v218
; __device__ __forceinline__ unsigned cvt_pk_bf16(float lo, float hi) { unsigned r; asm volatile("v_cvt_pk_bf16_f32 %0, %1, %2" : "=v"(r) : "v"(lo), "v"(hi)); return r; }
; __device__ __forceinline__ float bf_lo(unsigned w) { return __uint_as_float(w << 16); }
; __device__ __forceinline__ float bf_hi(unsigned w) { return __uint_as_float(w & 0xffff0000u); }
;     __device__ __forceinline__ void operator()(const f32x4 (&acc)[2][2][4][2], const Unit& u, int wr, int wc, int fr, int fq) const {
;     ...
;             for (int m = 0; m < 4; ++m)
; #pragma unroll
;                 for (int bj = 0; bj < 2; ++bj) { const int row = row0 + ai * HALF + m * 16, col = col0 + bj * HALF; const u32x4 g4 = gv[m][bj];
;                     const f32x4 a0 = acc[ai][bj][m][0], a1 = acc[ai][bj][m][1];
;                     float f0 = a0[0] * bf_lo(g4.x), f1 = a0[1] * bf_hi(g4.x), f2 = a0[2] * bf_lo(g4.y), f3 = a0[3] * bf_hi(g4.y);
;                     float f4 = a1[0] * bf_lo(g4.z), f5 = a1[1] * bf_hi(g4.z), f6 = a1[2] * bf_lo(g4.w), f7 = a1[3] * bf_hi(g4.w);
;                     if (br > 0) {
;                         const unsigned p0 = (unsigned)q0[m][bj], p1 = (unsigned)(q0[m][bj] >> 32), p2 = (unsigned)q1[m][bj], p3 = (unsigned)(q1[m][bj] >> 32);
;                         f0 += bf_lo(p0); f1 += bf_hi(p0); f2 += bf_lo(p1); f3 += bf_hi(p1); f4 += bf_lo(p2); f5 += bf_hi(p2); f6 += bf_lo(p3); f7 += bf_hi(p3);
;                     }
;                     u32x4 w; w.x = cvt_pk_bf16(f0, f1); w.y = cvt_pk_bf16(f2, f3); w.z = cvt_pk_bf16(f4, f5); w.w = cvt_pk_bf16(f6, f7);
;                     *(u32x4*)(Mg + (size_t)row * DM + col) = w; }
;             asm volatile("" ::: "memory"); }
	v_max_f32_e32 v219, 0x21800000, v219
	v_pk_mul_f32 v[30:31], v[30:31], v[218:219]
	v_lshlrev_b32_e32 v228, 16, v147
	v_and_b32_e32 v229, 0xffff0000, v147
	v_max_f32_e32 v228, 0x21800000, v228
	v_max_f32_e32 v229, 0x21800000, v229
	v_pk_mul_f32 v[32:33], v[32:33], v[228:229]
	v_lshlrev_b32_e32 v218, 16, v148
	v_and_b32_e32 v219, 0xffff0000, v148
	v_max_f32_e32 v218, 0x21800000, v218
	v_max_f32_e32 v219, 0x21800000, v219
	v_pk_mul_f32 v[26:27], v[26:27], v[218:219]
	v_lshlrev_b32_e32 v228, 16, v149
	v_and_b32_e32 v229, 0xffff0000, v149
	v_max_f32_e32 v228, 0x21800000, v228
	v_max_f32_e32 v229, 0x21800000, v229
	v_pk_mul_f32 v[28:29], v[28:29], v[228:229]
	v_cvt_pk_bf16_f32 v30, v30, v31
	v_cvt_pk_bf16_f32 v31, v32, v33
	v_cvt_pk_bf16_f32 v32, v26, v27
	v_cvt_pk_bf16_f32 v33, v28, v29
	v_lshl_add_u64 v[226:227], v[226:227], 0, s[46:47]
	global_store_dwordx4 v[226:227], v[30:33], off
	v_lshlrev_b32_e32 v218, 16, v150
	v_and_b32_e32 v219, 0xffff0000, v150
	v_max_f32_e32 v218, 0x21800000, v218
	v_max_f32_e32 v219, 0x21800000, v219
	v_pk_mul_f32 v[22:23], v[22:23], v[218:219]
	v_lshlrev_b32_e32 v228, 16, v151
	v_and_b32_e32 v229, 0xffff0000, v151
	v_max_f32_e32 v228, 0x21800000, v228
	v_max_f32_e32 v229, 0x21800000, v229
	v_pk_mul_f32 v[24:25], v[24:25], v[228:229]
	v_lshlrev_b32_e32 v218, 16, v152
	v_and_b32_e32 v219, 0xffff0000, v152
	v_max_f32_e32 v218, 0x21800000, v218
	v_max_f32_e32 v219, 0x21800000, v219
	v_pk_mul_f32 v[18:19], v[18:19], v[218:219]
	v_lshlrev_b32_e32 v228, 16, v153
	v_and_b32_e32 v229, 0xffff0000, v153
	v_max_f32_e32 v228, 0x21800000, v228
	v_max_f32_e32 v229, 0x21800000, v229
	v_pk_mul_f32 v[20:21], v[20:21], v[228:229]
	v_cvt_pk_bf16_f32 v22, v22, v23
	v_cvt_pk_bf16_f32 v23, v24, v25
	v_cvt_pk_bf16_f32 v24, v18, v19
	v_cvt_pk_bf16_f32 v25, v20, v21
	global_store_dwordx4 v[226:227], v[22:25], off offset:256
	v_lshlrev_b32_e32 v218, 16, v154
	v_and_b32_e32 v219, 0xffff0000, v154
	v_max_f32_e32 v218, 0x21800000, v218
	v_max_f32_e32 v219, 0x21800000, v219
	v_pk_mul_f32 v[14:15], v[14:15], v[218:219]
	v_lshlrev_b32_e32 v228, 16, v155
	v_and_b32_e32 v229, 0xffff0000, v155
	v_max_f32_e32 v228, 0x21800000, v228
	v_max_f32_e32 v229, 0x21800000, v229
	v_pk_mul_f32 v[16:17], v[16:17], v[228:229]
	v_lshlrev_b32_e32 v218, 16, v156
	v_and_b32_e32 v219, 0xffff0000, v156
	v_max_f32_e32 v218, 0x21800000, v218
	v_max_f32_e32 v219, 0x21800000, v219
	v_pk_mul_f32 v[10:11], v[10:11], v[218:219]
	v_lshlrev_b32_e32 v228, 16, v157
	v_and_b32_e32 v229, 0xffff0000, v157
	v_max_f32_e32 v228, 0x21800000, v228
	v_max_f32_e32 v229, 0x21800000, v229
	v_pk_mul_f32 v[12:13], v[12:13], v[228:229]
	v_cvt_pk_bf16_f32 v14, v14, v15
	v_cvt_pk_bf16_f32 v15, v16, v17
	v_cvt_pk_bf16_f32 v16, v10, v11
	v_cvt_pk_bf16_f32 v17, v12, v13
	v_lshl_add_u64 v[226:227], v[226:227], 0, s[46:47]
	global_store_dwordx4 v[226:227], v[14:17], off
	v_lshlrev_b32_e32 v218, 16, v158
	v_and_b32_e32 v219, 0xffff0000, v158
	v_max_f32_e32 v218, 0x21800000, v218
	v_max_f32_e32 v219, 0x21800000, v219
	v_pk_mul_f32 v[6:7], v[6:7], v[218:219]
	v_lshlrev_b32_e32 v228, 16, v159
	v_and_b32_e32 v229, 0xffff0000, v159
	v_max_f32_e32 v228, 0x21800000, v228
	v_max_f32_e32 v229, 0x21800000, v229
	v_pk_mul_f32 v[8:9], v[8:9], v[228:229]
	v_lshlrev_b32_e32 v218, 16, v160
	v_and_b32_e32 v219, 0xffff0000, v160
	v_max_f32_e32 v218, 0x21800000, v218
	v_max_f32_e32 v219, 0x21800000, v219
	v_pk_mul_f32 v[2:3], v[2:3], v[218:219]
	v_lshlrev_b32_e32 v228, 16, v161
	v_and_b32_e32 v229, 0xffff0000, v161
	v_max_f32_e32 v228, 0x21800000, v228
	v_max_f32_e32 v229, 0x21800000, v229
	v_pk_mul_f32 v[4:5], v[4:5], v[228:229]
	v_cvt_pk_bf16_f32 v6, v6, v7
	v_cvt_pk_bf16_f32 v7, v8, v9
	v_cvt_pk_bf16_f32 v8, v2, v3
	v_cvt_pk_bf16_f32 v9, v4, v5
	global_store_dwordx4 v[226:227], v[6:9], off offset:256
.Lrb_tail:
	s_andn2_b64 vcc, exec, s[6:7]
	s_mov_b64 s[6:7], -1
	s_cbranch_vccnz .LBB0_78
	s_andn2_b64 vcc, exec, s[10:11]
	s_cbranch_vccnz .LBB0_77
	s_barrier
	s_branch .LBB0_77
